# S5 pair mode: 4 Hs buffers, tail lags 2 chunks, one s_barrier per 2 chunks (128 instead of 256 per phase)
# speedup vs baseline: 1.0011x; 1.0011x over previous
.LBB0_88:
	s_andn2_b64 vcc, exec, s[2:3]
	s_cbranch_vccnz .LBB0_109
	s_movk_i32 s2, 0x180
	v_cmp_gt_i32_e32 vcc, s2, v132
	s_and_saveexec_b64 s[46:47], vcc
	s_cbranch_execz .LBB0_108
	v_mov_b32_e32 v211, v134
	v_readfirstlane_b32 s60, v132
	s_cmpk_lt_u32 s60, 0x80
	s_cbranch_scc0 .LS5R_nomap
	s_bitcmp1_b32 s60, 0
	s_cbranch_scc0 .LS5R_lat
	s_movk_i32 s61, 0x80

.LS5Q_common:
	s_movk_i32 s20, 0x4400
	s_bitcmp1_b32 s60, 1
	s_cbranch_scc0 .LS5Z_pos
	s_movk_i32 s20, 0xbc00
.LS5Z_pos:
	v_add_u32_e32 v174, s20, v172
	v_add_u32_e32 v175, s20, v173
	v_lshl_add_u64 v[248:249], v[248:249], 0, s[50:51]
	global_load_dwordx4 v[110:113], v[248:249], off offset:16
	global_load_dwordx4 v[106:109], v[248:249], off
	s_nop 7
	s_bitcmp1_b32 s61, 6
	s_cbranch_scc1 .LS5Q_selB
	s_cmp_lg_u64 s[40:41], 0
	s_cbranch_scc1 .LS5Q_loopr0d0
	s_branch .LS5Q_loopr0d1

.LS5Q_loopr1d1:
	s_cmp_lt_u32 s28, 4
	s_cbranch_scc0 .LS5Q_wr1d1j0
	s_waitcnt vmcnt(2)
.LS5Q_wr1d1j0:
	s_waitcnt vmcnt(4)
	v_cvt_pk_bf16_f32 v212, v102, v103
	v_cvt_pk_bf16_f32 v213, v104, v105
	v_cvt_pk_bf16_f32 v214, v98, v99
	v_cvt_pk_bf16_f32 v215, v100, v101
	s_add_u32 s20, s28, 3
	s_cmp_lt_u32 s20, s52
	s_cselect_b64 s[58:59], s[50:51], 0
	v_lshl_add_u64 v[248:249], v[248:249], 0, s[58:59]
	global_load_dwordx4 v[98:101], v[248:249], off offset:16
	global_load_dwordx4 v[102:105], v[248:249], off
	ds_read_b128 v[216:219], v175 offset:0
	ds_read_b128 v[220:223], v175 offset:64
	ds_read_b128 v[224:227], v175 offset:128
	ds_read_b128 v[228:231], v175 offset:192
	v_fmac_f32_e32 v49, v154, v180
	v_fmac_f32_e32 v65, v154, v176
	v_fma_f32 v49, -v155, v176, v49
	v_fmac_f32_e32 v65, v155, v180
	v_mfma_f32_32x32x16_bf16 v[2:17], v[212:215], v[70:73], 0
	v_fmac_f32_e32 v48, v154, v49
	v_fmac_f32_e32 v64, v154, v65
	v_cvt_pk_bf16_f32 v184, v49, v65
	v_fma_f32 v48, -v155, v65, v48
	v_fmac_f32_e32 v64, v155, v49
	ds_write_b32 v172, v184 offset:4080
	v_fmac_f32_e32 v47, v154, v48
	v_fmac_f32_e32 v63, v154, v64
	v_cvt_pk_bf16_f32 v185, v48, v64
	v_fma_f32 v47, -v155, v64, v47
	v_fmac_f32_e32 v63, v155, v48
	ds_write_b32 v172, v185 offset:3808
	v_mfma_f32_32x32x16_bf16 v[18:33], v[212:215], v[78:81], 0
	v_fmac_f32_e32 v46, v154, v47
	v_fmac_f32_e32 v62, v154, v63
	v_cvt_pk_bf16_f32 v184, v47, v63
	v_fma_f32 v46, -v155, v63, v46
	v_fmac_f32_e32 v62, v155, v47
	ds_write_b32 v172, v184 offset:3536
	v_fmac_f32_e32 v45, v154, v46
	v_fmac_f32_e32 v61, v154, v62
	v_cvt_pk_bf16_f32 v185, v46, v62
	v_fma_f32 v45, -v155, v62, v45
	v_fmac_f32_e32 v61, v155, v46
	ds_write_b32 v172, v185 offset:3264
	s_waitcnt lgkmcnt(4)
	v_mfma_f32_16x16x32_bf16 v[232:235], v[82:85], v[216:219], 0
	v_fmac_f32_e32 v44, v154, v45
	v_fmac_f32_e32 v60, v154, v61
	v_cvt_pk_bf16_f32 v184, v45, v61
	v_fma_f32 v44, -v155, v61, v44
	v_fmac_f32_e32 v60, v155, v45
	ds_write_b32 v172, v184 offset:2992
	v_mfma_f32_16x16x32_bf16 v[232:235], v[86:89], v[220:223], v[232:235]
	v_fmac_f32_e32 v43, v154, v44
	v_fmac_f32_e32 v59, v154, v60
	v_cvt_pk_bf16_f32 v185, v44, v60
	v_fma_f32 v43, -v155, v60, v43
	v_fmac_f32_e32 v59, v155, v44
	ds_write_b32 v172, v185 offset:2720
	v_mfma_f32_16x16x32_bf16 v[232:235], v[90:93], v[224:227], v[232:235]
	v_fmac_f32_e32 v42, v154, v43
	v_fmac_f32_e32 v58, v154, v59
	v_cvt_pk_bf16_f32 v184, v43, v59
	v_fma_f32 v42, -v155, v59, v42
	v_fmac_f32_e32 v58, v155, v43
	ds_write_b32 v172, v184 offset:2448
	v_mfma_f32_16x16x32_bf16 v[232:235], v[94:97], v[228:231], v[232:235]
	v_fmac_f32_e32 v41, v154, v42
	v_fmac_f32_e32 v57, v154, v58
	v_cvt_pk_bf16_f32 v185, v42, v58
	v_fma_f32 v41, -v155, v58, v41
	v_fmac_f32_e32 v57, v155, v42
	ds_write_b32 v172, v185 offset:2176
	v_fmac_f32_e32 v40, v154, v41
	v_fmac_f32_e32 v56, v154, v57
	v_cvt_pk_bf16_f32 v184, v41, v57
	v_fma_f32 v40, -v155, v57, v40
	v_fmac_f32_e32 v56, v155, v41
	ds_write_b32 v172, v184 offset:1904
	v_fmac_f32_e32 v39, v154, v40
	v_fmac_f32_e32 v55, v154, v56
	v_cvt_pk_bf16_f32 v185, v40, v56
	v_fma_f32 v39, -v155, v56, v39
	v_fmac_f32_e32 v55, v155, v40
	ds_write_b32 v172, v185 offset:1632
	s_cmp_lt_u32 s28, 2
	s_cbranch_scc1 .LS5Q_nstr1d1j0
	global_store_dwordx4 v[240:241], v[232:235], off
	v_lshl_add_u64 v[240:241], v[240:241], 0, s[50:51]
.LS5Q_nstr1d1j0:
	v_fmac_f32_e32 v38, v154, v39
	v_fmac_f32_e32 v54, v154, v55
	v_cvt_pk_bf16_f32 v184, v39, v55
	v_fma_f32 v38, -v155, v55, v38
	v_fmac_f32_e32 v54, v155, v39
	ds_write_b32 v172, v184 offset:1360
	v_fmac_f32_e32 v37, v154, v38
	v_fmac_f32_e32 v53, v154, v54
	v_cvt_pk_bf16_f32 v185, v38, v54
	v_fma_f32 v37, -v155, v54, v37
	v_fmac_f32_e32 v53, v155, v38
	ds_write_b32 v172, v185 offset:1088
	v_fmac_f32_e32 v36, v154, v37
	v_fmac_f32_e32 v52, v154, v53
	v_cvt_pk_bf16_f32 v184, v37, v53
	v_fma_f32 v36, -v155, v53, v36
	v_fmac_f32_e32 v52, v155, v37
	ds_write_b32 v172, v184 offset:816
	v_fmac_f32_e32 v35, v154, v36
	v_fmac_f32_e32 v51, v154, v52
	v_cvt_pk_bf16_f32 v185, v36, v52
	v_fma_f32 v35, -v155, v52, v35
	v_fmac_f32_e32 v51, v155, v36
	ds_write_b32 v172, v185 offset:544
	v_fma_f32 v180, v154, v35, v34
	v_fma_f32 v176, v154, v51, v50
	v_cvt_pk_bf16_f32 v184, v35, v51
	v_fma_f32 v180, -v155, v51, v180
	v_fmac_f32_e32 v176, v155, v35
	ds_write_b32 v172, v184 offset:272
	v_cvt_pk_bf16_f32 v185, v180, v176
	ds_write_b32 v172, v185 offset:0
	s_add_u32 s28, s28, 1
	s_cmp_lt_u32 s28, 4
	s_cbranch_scc0 .LS5Q_wr1d1j1
	s_waitcnt vmcnt(2)
.LS5Q_wr1d1j1:
	s_waitcnt vmcnt(4)
	v_cvt_pk_bf16_f32 v212, v106, v107
	v_cvt_pk_bf16_f32 v213, v108, v109
	v_cvt_pk_bf16_f32 v214, v110, v111
	v_cvt_pk_bf16_f32 v215, v112, v113
	s_add_u32 s20, s28, 3
	s_cmp_lt_u32 s20, s52
	s_cselect_b64 s[58:59], s[50:51], 0
	v_lshl_add_u64 v[248:249], v[248:249], 0, s[58:59]
	global_load_dwordx4 v[110:113], v[248:249], off offset:16
	global_load_dwordx4 v[106:109], v[248:249], off
	ds_read_b128 v[216:219], v175 offset:60416
	ds_read_b128 v[220:223], v175 offset:60480
	ds_read_b128 v[224:227], v175 offset:60544
	ds_read_b128 v[228:231], v175 offset:60608
	v_fmac_f32_e32 v17, v154, v180
	v_fmac_f32_e32 v33, v154, v176
	v_fma_f32 v17, -v155, v176, v17
	v_fmac_f32_e32 v33, v155, v180
	v_mfma_f32_32x32x16_bf16 v[34:49], v[212:215], v[70:73], 0
	v_fmac_f32_e32 v16, v154, v17
	v_fmac_f32_e32 v32, v154, v33
	v_cvt_pk_bf16_f32 v184, v17, v33
	v_fma_f32 v16, -v155, v33, v16
	v_fmac_f32_e32 v32, v155, v17
	ds_write_b32 v172, v184 offset:64496
	v_fmac_f32_e32 v15, v154, v16
	v_fmac_f32_e32 v31, v154, v32
	v_cvt_pk_bf16_f32 v185, v16, v32
	v_fma_f32 v15, -v155, v32, v15
	v_fmac_f32_e32 v31, v155, v16
	ds_write_b32 v172, v185 offset:64224
	v_mfma_f32_32x32x16_bf16 v[50:65], v[212:215], v[78:81], 0
	v_fmac_f32_e32 v14, v154, v15
	v_fmac_f32_e32 v30, v154, v31
	v_cvt_pk_bf16_f32 v184, v15, v31
	v_fma_f32 v14, -v155, v31, v14
	v_fmac_f32_e32 v30, v155, v15
	ds_write_b32 v172, v184 offset:63952
	v_fmac_f32_e32 v13, v154, v14
	v_fmac_f32_e32 v29, v154, v30
	v_cvt_pk_bf16_f32 v185, v14, v30
	v_fma_f32 v13, -v155, v30, v13
	v_fmac_f32_e32 v29, v155, v14
	ds_write_b32 v172, v185 offset:63680
	s_waitcnt lgkmcnt(4)
	v_mfma_f32_16x16x32_bf16 v[232:235], v[82:85], v[216:219], 0
	v_fmac_f32_e32 v12, v154, v13
	v_fmac_f32_e32 v28, v154, v29
	v_cvt_pk_bf16_f32 v184, v13, v29
	v_fma_f32 v12, -v155, v29, v12
	v_fmac_f32_e32 v28, v155, v13
	ds_write_b32 v172, v184 offset:63408
	v_mfma_f32_16x16x32_bf16 v[232:235], v[86:89], v[220:223], v[232:235]
	v_fmac_f32_e32 v11, v154, v12
	v_fmac_f32_e32 v27, v154, v28
	v_cvt_pk_bf16_f32 v185, v12, v28
	v_fma_f32 v11, -v155, v28, v11
	v_fmac_f32_e32 v27, v155, v12
	ds_write_b32 v172, v185 offset:63136
	v_mfma_f32_16x16x32_bf16 v[232:235], v[90:93], v[224:227], v[232:235]
	v_fmac_f32_e32 v10, v154, v11
	v_fmac_f32_e32 v26, v154, v27
	v_cvt_pk_bf16_f32 v184, v11, v27
	v_fma_f32 v10, -v155, v27, v10
	v_fmac_f32_e32 v26, v155, v11
	ds_write_b32 v172, v184 offset:62864
	v_mfma_f32_16x16x32_bf16 v[232:235], v[94:97], v[228:231], v[232:235]
	v_fmac_f32_e32 v9, v154, v10
	v_fmac_f32_e32 v25, v154, v26
	v_cvt_pk_bf16_f32 v185, v10, v26
	v_fma_f32 v9, -v155, v26, v9
	v_fmac_f32_e32 v25, v155, v10
	ds_write_b32 v172, v185 offset:62592
	v_fmac_f32_e32 v8, v154, v9
	v_fmac_f32_e32 v24, v154, v25
	v_cvt_pk_bf16_f32 v184, v9, v25
	v_fma_f32 v8, -v155, v25, v8
	v_fmac_f32_e32 v24, v155, v9
	ds_write_b32 v172, v184 offset:62320
	v_fmac_f32_e32 v7, v154, v8
	v_fmac_f32_e32 v23, v154, v24
	v_cvt_pk_bf16_f32 v185, v8, v24
	v_fma_f32 v7, -v155, v24, v7
	v_fmac_f32_e32 v23, v155, v8
	ds_write_b32 v172, v185 offset:62048
	s_cmp_lt_u32 s28, 2
	s_cbranch_scc1 .LS5Q_nstr1d1j1
	global_store_dwordx4 v[240:241], v[232:235], off
	v_lshl_add_u64 v[240:241], v[240:241], 0, s[50:51]
.LS5Q_nstr1d1j1:
	v_fmac_f32_e32 v6, v154, v7
	v_fmac_f32_e32 v22, v154, v23
	v_cvt_pk_bf16_f32 v184, v7, v23
	v_fma_f32 v6, -v155, v23, v6
	v_fmac_f32_e32 v22, v155, v7
	ds_write_b32 v172, v184 offset:61776
	v_fmac_f32_e32 v5, v154, v6
	v_fmac_f32_e32 v21, v154, v22
	v_cvt_pk_bf16_f32 v185, v6, v22
	v_fma_f32 v5, -v155, v22, v5
	v_fmac_f32_e32 v21, v155, v6
	ds_write_b32 v172, v185 offset:61504
	v_fmac_f32_e32 v4, v154, v5
	v_fmac_f32_e32 v20, v154, v21
	v_cvt_pk_bf16_f32 v184, v5, v21
	v_fma_f32 v4, -v155, v21, v4
	v_fmac_f32_e32 v20, v155, v5
	ds_write_b32 v172, v184 offset:61232
	v_fmac_f32_e32 v3, v154, v4
	v_fmac_f32_e32 v19, v154, v20
	v_cvt_pk_bf16_f32 v185, v4, v20
	v_fma_f32 v3, -v155, v20, v3
	v_fmac_f32_e32 v19, v155, v4
	ds_write_b32 v172, v185 offset:60960
	v_fma_f32 v180, v154, v3, v2
	v_fma_f32 v176, v154, v19, v18
	v_cvt_pk_bf16_f32 v184, v3, v19
	v_fma_f32 v180, -v155, v19, v180
	v_fmac_f32_e32 v176, v155, v3
	ds_write_b32 v172, v184 offset:60688
	v_cvt_pk_bf16_f32 v185, v180, v176
	ds_write_b32 v172, v185 offset:60416
	s_waitcnt lgkmcnt(0)
	s_barrier
	s_add_u32 s28, s28, 1
	s_cmp_lt_u32 s28, 4
	s_cbranch_scc0 .LS5Q_wr1d1j2
	s_waitcnt vmcnt(2)
.LS5Q_wr1d1j2:
	s_waitcnt vmcnt(4)
	v_cvt_pk_bf16_f32 v212, v102, v103
	v_cvt_pk_bf16_f32 v213, v104, v105
	v_cvt_pk_bf16_f32 v214, v98, v99
	v_cvt_pk_bf16_f32 v215, v100, v101
	s_add_u32 s20, s28, 3
	s_cmp_lt_u32 s20, s52
	s_cselect_b64 s[58:59], s[50:51], 0
	v_lshl_add_u64 v[248:249], v[248:249], 0, s[58:59]
	global_load_dwordx4 v[98:101], v[248:249], off offset:16
	global_load_dwordx4 v[102:105], v[248:249], off
	ds_read_b128 v[216:219], v173 offset:0
	ds_read_b128 v[220:223], v173 offset:64
	ds_read_b128 v[224:227], v173 offset:128
	ds_read_b128 v[228:231], v173 offset:192
	v_fmac_f32_e32 v49, v154, v180
	v_fmac_f32_e32 v65, v154, v176
	v_fma_f32 v49, -v155, v176, v49
	v_fmac_f32_e32 v65, v155, v180
	v_mfma_f32_32x32x16_bf16 v[2:17], v[212:215], v[70:73], 0
	v_fmac_f32_e32 v48, v154, v49
	v_fmac_f32_e32 v64, v154, v65
	v_cvt_pk_bf16_f32 v184, v49, v65
	v_fma_f32 v48, -v155, v65, v48
	v_fmac_f32_e32 v64, v155, v49
	ds_write_b32 v174, v184 offset:4080
	v_fmac_f32_e32 v47, v154, v48
	v_fmac_f32_e32 v63, v154, v64
	v_cvt_pk_bf16_f32 v185, v48, v64
	v_fma_f32 v47, -v155, v64, v47
	v_fmac_f32_e32 v63, v155, v48
	ds_write_b32 v174, v185 offset:3808
	v_mfma_f32_32x32x16_bf16 v[18:33], v[212:215], v[78:81], 0
	v_fmac_f32_e32 v46, v154, v47
	v_fmac_f32_e32 v62, v154, v63
	v_cvt_pk_bf16_f32 v184, v47, v63
	v_fma_f32 v46, -v155, v63, v46
	v_fmac_f32_e32 v62, v155, v47
	ds_write_b32 v174, v184 offset:3536
	v_fmac_f32_e32 v45, v154, v46
	v_fmac_f32_e32 v61, v154, v62
	v_cvt_pk_bf16_f32 v185, v46, v62
	v_fma_f32 v45, -v155, v62, v45
	v_fmac_f32_e32 v61, v155, v46
	ds_write_b32 v174, v185 offset:3264
	s_waitcnt lgkmcnt(4)
	v_mfma_f32_16x16x32_bf16 v[232:235], v[82:85], v[216:219], 0
	v_fmac_f32_e32 v44, v154, v45
	v_fmac_f32_e32 v60, v154, v61
	v_cvt_pk_bf16_f32 v184, v45, v61
	v_fma_f32 v44, -v155, v61, v44
	v_fmac_f32_e32 v60, v155, v45
	ds_write_b32 v174, v184 offset:2992
	v_mfma_f32_16x16x32_bf16 v[232:235], v[86:89], v[220:223], v[232:235]
	v_fmac_f32_e32 v43, v154, v44
	v_fmac_f32_e32 v59, v154, v60
	v_cvt_pk_bf16_f32 v185, v44, v60
	v_fma_f32 v43, -v155, v60, v43
	v_fmac_f32_e32 v59, v155, v44
	ds_write_b32 v174, v185 offset:2720
	v_mfma_f32_16x16x32_bf16 v[232:235], v[90:93], v[224:227], v[232:235]
	v_fmac_f32_e32 v42, v154, v43
	v_fmac_f32_e32 v58, v154, v59
	v_cvt_pk_bf16_f32 v184, v43, v59
	v_fma_f32 v42, -v155, v59, v42
	v_fmac_f32_e32 v58, v155, v43
	ds_write_b32 v174, v184 offset:2448
	v_mfma_f32_16x16x32_bf16 v[232:235], v[94:97], v[228:231], v[232:235]
	v_fmac_f32_e32 v41, v154, v42
	v_fmac_f32_e32 v57, v154, v58
	v_cvt_pk_bf16_f32 v185, v42, v58
	v_fma_f32 v41, -v155, v58, v41
	v_fmac_f32_e32 v57, v155, v42
	ds_write_b32 v174, v185 offset:2176
	v_fmac_f32_e32 v40, v154, v41
	v_fmac_f32_e32 v56, v154, v57
	v_cvt_pk_bf16_f32 v184, v41, v57
	v_fma_f32 v40, -v155, v57, v40
	v_fmac_f32_e32 v56, v155, v41
	ds_write_b32 v174, v184 offset:1904
	v_fmac_f32_e32 v39, v154, v40
	v_fmac_f32_e32 v55, v154, v56
	v_cvt_pk_bf16_f32 v185, v40, v56
	v_fma_f32 v39, -v155, v56, v39
	v_fmac_f32_e32 v55, v155, v40
	ds_write_b32 v174, v185 offset:1632
	global_store_dwordx4 v[240:241], v[232:235], off
	v_lshl_add_u64 v[240:241], v[240:241], 0, s[50:51]
	v_fmac_f32_e32 v38, v154, v39
	v_fmac_f32_e32 v54, v154, v55
	v_cvt_pk_bf16_f32 v184, v39, v55
	v_fma_f32 v38, -v155, v55, v38
	v_fmac_f32_e32 v54, v155, v39
	ds_write_b32 v174, v184 offset:1360
	v_fmac_f32_e32 v37, v154, v38
	v_fmac_f32_e32 v53, v154, v54
	v_cvt_pk_bf16_f32 v185, v38, v54
	v_fma_f32 v37, -v155, v54, v37
	v_fmac_f32_e32 v53, v155, v38
	ds_write_b32 v174, v185 offset:1088
	v_fmac_f32_e32 v36, v154, v37
	v_fmac_f32_e32 v52, v154, v53
	v_cvt_pk_bf16_f32 v184, v37, v53
	v_fma_f32 v36, -v155, v53, v36
	v_fmac_f32_e32 v52, v155, v37
	ds_write_b32 v174, v184 offset:816
	v_fmac_f32_e32 v35, v154, v36
	v_fmac_f32_e32 v51, v154, v52
	v_cvt_pk_bf16_f32 v185, v36, v52
	v_fma_f32 v35, -v155, v52, v35
	v_fmac_f32_e32 v51, v155, v36
	ds_write_b32 v174, v185 offset:544
	v_fma_f32 v180, v154, v35, v34
	v_fma_f32 v176, v154, v51, v50
	v_cvt_pk_bf16_f32 v184, v35, v51
	v_fma_f32 v180, -v155, v51, v180
	v_fmac_f32_e32 v176, v155, v35
	ds_write_b32 v174, v184 offset:272
	v_cvt_pk_bf16_f32 v185, v180, v176
	ds_write_b32 v174, v185 offset:0
	s_add_u32 s28, s28, 1
	s_cmp_lt_u32 s28, 4
	s_cbranch_scc0 .LS5Q_wr1d1j3
	s_waitcnt vmcnt(2)
.LS5Q_wr1d1j3:
	s_waitcnt vmcnt(4)
	v_cvt_pk_bf16_f32 v212, v106, v107
	v_cvt_pk_bf16_f32 v213, v108, v109
	v_cvt_pk_bf16_f32 v214, v110, v111
	v_cvt_pk_bf16_f32 v215, v112, v113
	s_add_u32 s20, s28, 3
	s_cmp_lt_u32 s20, s52
	s_cselect_b64 s[58:59], s[50:51], 0
	v_lshl_add_u64 v[248:249], v[248:249], 0, s[58:59]
	global_load_dwordx4 v[110:113], v[248:249], off offset:16
	global_load_dwordx4 v[106:109], v[248:249], off
	ds_read_b128 v[216:219], v173 offset:60416
	ds_read_b128 v[220:223], v173 offset:60480
	ds_read_b128 v[224:227], v173 offset:60544
	ds_read_b128 v[228:231], v173 offset:60608
	v_fmac_f32_e32 v17, v154, v180
	v_fmac_f32_e32 v33, v154, v176
	v_fma_f32 v17, -v155, v176, v17
	v_fmac_f32_e32 v33, v155, v180
	v_mfma_f32_32x32x16_bf16 v[34:49], v[212:215], v[70:73], 0
	v_fmac_f32_e32 v16, v154, v17
	v_fmac_f32_e32 v32, v154, v33
	v_cvt_pk_bf16_f32 v184, v17, v33
	v_fma_f32 v16, -v155, v33, v16
	v_fmac_f32_e32 v32, v155, v17
	ds_write_b32 v174, v184 offset:64496
	v_fmac_f32_e32 v15, v154, v16
	v_fmac_f32_e32 v31, v154, v32
	v_cvt_pk_bf16_f32 v185, v16, v32
	v_fma_f32 v15, -v155, v32, v15
	v_fmac_f32_e32 v31, v155, v16
	ds_write_b32 v174, v185 offset:64224
	v_mfma_f32_32x32x16_bf16 v[50:65], v[212:215], v[78:81], 0
	v_fmac_f32_e32 v14, v154, v15
	v_fmac_f32_e32 v30, v154, v31
	v_cvt_pk_bf16_f32 v184, v15, v31
	v_fma_f32 v14, -v155, v31, v14
	v_fmac_f32_e32 v30, v155, v15
	ds_write_b32 v174, v184 offset:63952
	v_fmac_f32_e32 v13, v154, v14
	v_fmac_f32_e32 v29, v154, v30
	v_cvt_pk_bf16_f32 v185, v14, v30
	v_fma_f32 v13, -v155, v30, v13
	v_fmac_f32_e32 v29, v155, v14
	ds_write_b32 v174, v185 offset:63680
	s_waitcnt lgkmcnt(4)
	v_mfma_f32_16x16x32_bf16 v[232:235], v[82:85], v[216:219], 0
	v_fmac_f32_e32 v12, v154, v13
	v_fmac_f32_e32 v28, v154, v29
	v_cvt_pk_bf16_f32 v184, v13, v29
	v_fma_f32 v12, -v155, v29, v12
	v_fmac_f32_e32 v28, v155, v13
	ds_write_b32 v174, v184 offset:63408
	v_mfma_f32_16x16x32_bf16 v[232:235], v[86:89], v[220:223], v[232:235]
	v_fmac_f32_e32 v11, v154, v12
	v_fmac_f32_e32 v27, v154, v28
	v_cvt_pk_bf16_f32 v185, v12, v28
	v_fma_f32 v11, -v155, v28, v11
	v_fmac_f32_e32 v27, v155, v12
	ds_write_b32 v174, v185 offset:63136
	v_mfma_f32_16x16x32_bf16 v[232:235], v[90:93], v[224:227], v[232:235]
	v_fmac_f32_e32 v10, v154, v11
	v_fmac_f32_e32 v26, v154, v27
	v_cvt_pk_bf16_f32 v184, v11, v27
	v_fma_f32 v10, -v155, v27, v10
	v_fmac_f32_e32 v26, v155, v11
	ds_write_b32 v174, v184 offset:62864
	v_mfma_f32_16x16x32_bf16 v[232:235], v[94:97], v[228:231], v[232:235]
	v_fmac_f32_e32 v9, v154, v10
	v_fmac_f32_e32 v25, v154, v26
	v_cvt_pk_bf16_f32 v185, v10, v26
	v_fma_f32 v9, -v155, v26, v9
	v_fmac_f32_e32 v25, v155, v10
	ds_write_b32 v174, v185 offset:62592
	v_fmac_f32_e32 v8, v154, v9
	v_fmac_f32_e32 v24, v154, v25
	v_cvt_pk_bf16_f32 v184, v9, v25
	v_fma_f32 v8, -v155, v25, v8
	v_fmac_f32_e32 v24, v155, v9
	ds_write_b32 v174, v184 offset:62320
	v_fmac_f32_e32 v7, v154, v8
	v_fmac_f32_e32 v23, v154, v24
	v_cvt_pk_bf16_f32 v185, v8, v24
	v_fma_f32 v7, -v155, v24, v7
	v_fmac_f32_e32 v23, v155, v8
	ds_write_b32 v174, v185 offset:62048
	global_store_dwordx4 v[240:241], v[232:235], off
	v_lshl_add_u64 v[240:241], v[240:241], 0, s[50:51]
	v_fmac_f32_e32 v6, v154, v7
	v_fmac_f32_e32 v22, v154, v23
	v_cvt_pk_bf16_f32 v184, v7, v23
	v_fma_f32 v6, -v155, v23, v6
	v_fmac_f32_e32 v22, v155, v7
	ds_write_b32 v174, v184 offset:61776
	v_fmac_f32_e32 v5, v154, v6
	v_fmac_f32_e32 v21, v154, v22
	v_cvt_pk_bf16_f32 v185, v6, v22
	v_fma_f32 v5, -v155, v22, v5
	v_fmac_f32_e32 v21, v155, v6
	ds_write_b32 v174, v185 offset:61504
	v_fmac_f32_e32 v4, v154, v5
	v_fmac_f32_e32 v20, v154, v21
	v_cvt_pk_bf16_f32 v184, v5, v21
	v_fma_f32 v4, -v155, v21, v4
	v_fmac_f32_e32 v20, v155, v5
	ds_write_b32 v174, v184 offset:61232
	v_fmac_f32_e32 v3, v154, v4
	v_fmac_f32_e32 v19, v154, v20
	v_cvt_pk_bf16_f32 v185, v4, v20
	v_fma_f32 v3, -v155, v20, v3
	v_fmac_f32_e32 v19, v155, v4
	ds_write_b32 v174, v185 offset:60960
	v_fma_f32 v180, v154, v3, v2
	v_fma_f32 v176, v154, v19, v18
	v_cvt_pk_bf16_f32 v184, v3, v19
	v_fma_f32 v180, -v155, v19, v180
	v_fmac_f32_e32 v176, v155, v3
	ds_write_b32 v174, v184 offset:60688
	v_cvt_pk_bf16_f32 v185, v180, v176
	ds_write_b32 v174, v185 offset:60416
	s_waitcnt lgkmcnt(0)
	s_barrier
	s_add_u32 s28, s28, 1
	s_cmp_lt_u32 s28, s52
	s_cbranch_scc1 .LS5Q_loopr1d1
	s_branch .LS5Q_epi

.LS5Q_wr1d0j0:
	s_waitcnt vmcnt(4)
	v_cvt_pk_bf16_f32 v212, v102, v103
	v_cvt_pk_bf16_f32 v213, v104, v105
	v_cvt_pk_bf16_f32 v214, v98, v99
	v_cvt_pk_bf16_f32 v215, v100, v101
	s_add_u32 s20, s28, 3
	s_cmp_lt_u32 s20, s52
	s_cselect_b64 s[58:59], s[50:51], 0
	v_lshl_add_u64 v[248:249], v[248:249], 0, s[58:59]
	global_load_dwordx4 v[98:101], v[248:249], off offset:16
	global_load_dwordx4 v[102:105], v[248:249], off
	ds_read_b128 v[216:219], v175 offset:0
	ds_read_b128 v[220:223], v175 offset:64
	ds_read_b128 v[224:227], v175 offset:128
	ds_read_b128 v[228:231], v175 offset:192
	v_fmac_f32_e32 v34, v154, v180
	v_fmac_f32_e32 v50, v154, v176
	v_fma_f32 v34, -v155, v176, v34
	v_fmac_f32_e32 v50, v155, v180
	v_mfma_f32_32x32x16_bf16 v[2:17], v[212:215], v[70:73], 0
	v_fmac_f32_e32 v35, v154, v34
	v_fmac_f32_e32 v51, v154, v50
	v_cvt_pk_bf16_f32 v184, v34, v50
	v_fma_f32 v35, -v155, v50, v35
	v_fmac_f32_e32 v51, v155, v34
	ds_write_b32 v172, v184 offset:0
	v_fmac_f32_e32 v36, v154, v35
	v_fmac_f32_e32 v52, v154, v51
	v_cvt_pk_bf16_f32 v185, v35, v51
	v_fma_f32 v36, -v155, v51, v36
	v_fmac_f32_e32 v52, v155, v35
	ds_write_b32 v172, v185 offset:272
	v_mfma_f32_32x32x16_bf16 v[18:33], v[212:215], v[78:81], 0
	v_fmac_f32_e32 v37, v154, v36
	v_fmac_f32_e32 v53, v154, v52
	v_cvt_pk_bf16_f32 v184, v36, v52
	v_fma_f32 v37, -v155, v52, v37
	v_fmac_f32_e32 v53, v155, v36
	ds_write_b32 v172, v184 offset:544
	v_fmac_f32_e32 v38, v154, v37
	v_fmac_f32_e32 v54, v154, v53
	v_cvt_pk_bf16_f32 v185, v37, v53
	v_fma_f32 v38, -v155, v53, v38
	v_fmac_f32_e32 v54, v155, v37
	ds_write_b32 v172, v185 offset:816
	s_waitcnt lgkmcnt(4)
	v_mfma_f32_16x16x32_bf16 v[232:235], v[82:85], v[216:219], 0
	v_fmac_f32_e32 v39, v154, v38
	v_fmac_f32_e32 v55, v154, v54
	v_cvt_pk_bf16_f32 v184, v38, v54
	v_fma_f32 v39, -v155, v54, v39
	v_fmac_f32_e32 v55, v155, v38
	ds_write_b32 v172, v184 offset:1088
	v_mfma_f32_16x16x32_bf16 v[232:235], v[86:89], v[220:223], v[232:235]
	v_fmac_f32_e32 v40, v154, v39
	v_fmac_f32_e32 v56, v154, v55
	v_cvt_pk_bf16_f32 v185, v39, v55
	v_fma_f32 v40, -v155, v55, v40
	v_fmac_f32_e32 v56, v155, v39
	ds_write_b32 v172, v185 offset:1360
	v_mfma_f32_16x16x32_bf16 v[232:235], v[90:93], v[224:227], v[232:235]
	v_fmac_f32_e32 v41, v154, v40
	v_fmac_f32_e32 v57, v154, v56
	v_cvt_pk_bf16_f32 v184, v40, v56
	v_fma_f32 v41, -v155, v56, v41
	v_fmac_f32_e32 v57, v155, v40
	ds_write_b32 v172, v184 offset:1632
	v_mfma_f32_16x16x32_bf16 v[232:235], v[94:97], v[228:231], v[232:235]
	v_fmac_f32_e32 v42, v154, v41
	v_fmac_f32_e32 v58, v154, v57
	v_cvt_pk_bf16_f32 v185, v41, v57
	v_fma_f32 v42, -v155, v57, v42
	v_fmac_f32_e32 v58, v155, v41
	ds_write_b32 v172, v185 offset:1904
	v_fmac_f32_e32 v43, v154, v42
	v_fmac_f32_e32 v59, v154, v58
	v_cvt_pk_bf16_f32 v184, v42, v58
	v_fma_f32 v43, -v155, v58, v43
	v_fmac_f32_e32 v59, v155, v42
	ds_write_b32 v172, v184 offset:2176
	v_fmac_f32_e32 v44, v154, v43
	v_fmac_f32_e32 v60, v154, v59
	v_cvt_pk_bf16_f32 v185, v43, v59
	v_fma_f32 v44, -v155, v59, v44
	v_fmac_f32_e32 v60, v155, v43
	ds_write_b32 v172, v185 offset:2448
	s_cmp_lt_u32 s28, 2
	s_cbranch_scc1 .LS5Q_nstr1d0j0
	global_store_dwordx4 v[240:241], v[232:235], off
	v_lshl_add_u64 v[240:241], v[240:241], 0, s[50:51]
.LS5Q_nstr1d0j0:
	v_fmac_f32_e32 v45, v154, v44
	v_fmac_f32_e32 v61, v154, v60
	v_cvt_pk_bf16_f32 v184, v44, v60
	v_fma_f32 v45, -v155, v60, v45
	v_fmac_f32_e32 v61, v155, v44
	ds_write_b32 v172, v184 offset:2720
	v_fmac_f32_e32 v46, v154, v45
	v_fmac_f32_e32 v62, v154, v61
	v_cvt_pk_bf16_f32 v185, v45, v61
	v_fma_f32 v46, -v155, v61, v46
	v_fmac_f32_e32 v62, v155, v45
	ds_write_b32 v172, v185 offset:2992
	v_fmac_f32_e32 v47, v154, v46
	v_fmac_f32_e32 v63, v154, v62
	v_cvt_pk_bf16_f32 v184, v46, v62
	v_fma_f32 v47, -v155, v62, v47
	v_fmac_f32_e32 v63, v155, v46
	ds_write_b32 v172, v184 offset:3264
	v_fmac_f32_e32 v48, v154, v47
	v_fmac_f32_e32 v64, v154, v63
	v_cvt_pk_bf16_f32 v185, v47, v63
	v_fma_f32 v48, -v155, v63, v48
	v_fmac_f32_e32 v64, v155, v47
	ds_write_b32 v172, v185 offset:3536
	v_fma_f32 v180, v154, v48, v49
	v_fma_f32 v176, v154, v64, v65
	v_cvt_pk_bf16_f32 v184, v48, v64
	v_fma_f32 v180, -v155, v64, v180
	v_fmac_f32_e32 v176, v155, v48
	ds_write_b32 v172, v184 offset:3808
	v_cvt_pk_bf16_f32 v185, v180, v176
	ds_write_b32 v172, v185 offset:4080
	s_add_u32 s28, s28, 1
	s_cmp_lt_u32 s28, 4
	s_cbranch_scc0 .LS5Q_wr1d0j1
	s_waitcnt vmcnt(2)
.LS5Q_wr1d0j1:
	s_waitcnt vmcnt(4)
	v_cvt_pk_bf16_f32 v212, v106, v107
	v_cvt_pk_bf16_f32 v213, v108, v109
	v_cvt_pk_bf16_f32 v214, v110, v111
	v_cvt_pk_bf16_f32 v215, v112, v113
	s_add_u32 s20, s28, 3
	s_cmp_lt_u32 s20, s52
	s_cselect_b64 s[58:59], s[50:51], 0
	v_lshl_add_u64 v[248:249], v[248:249], 0, s[58:59]
	global_load_dwordx4 v[110:113], v[248:249], off offset:16
	global_load_dwordx4 v[106:109], v[248:249], off
	ds_read_b128 v[216:219], v175 offset:60416
	ds_read_b128 v[220:223], v175 offset:60480
	ds_read_b128 v[224:227], v175 offset:60544
	ds_read_b128 v[228:231], v175 offset:60608
	v_fmac_f32_e32 v2, v154, v180
	v_fmac_f32_e32 v18, v154, v176
	v_fma_f32 v2, -v155, v176, v2
	v_fmac_f32_e32 v18, v155, v180
	v_mfma_f32_32x32x16_bf16 v[34:49], v[212:215], v[70:73], 0
	v_fmac_f32_e32 v3, v154, v2
	v_fmac_f32_e32 v19, v154, v18
	v_cvt_pk_bf16_f32 v184, v2, v18
	v_fma_f32 v3, -v155, v18, v3
	v_fmac_f32_e32 v19, v155, v2
	ds_write_b32 v172, v184 offset:60416
	v_fmac_f32_e32 v4, v154, v3
	v_fmac_f32_e32 v20, v154, v19
	v_cvt_pk_bf16_f32 v185, v3, v19
	v_fma_f32 v4, -v155, v19, v4
	v_fmac_f32_e32 v20, v155, v3
	ds_write_b32 v172, v185 offset:60688
	v_mfma_f32_32x32x16_bf16 v[50:65], v[212:215], v[78:81], 0
	v_fmac_f32_e32 v5, v154, v4
	v_fmac_f32_e32 v21, v154, v20
	v_cvt_pk_bf16_f32 v184, v4, v20
	v_fma_f32 v5, -v155, v20, v5
	v_fmac_f32_e32 v21, v155, v4
	ds_write_b32 v172, v184 offset:60960
	v_fmac_f32_e32 v6, v154, v5
	v_fmac_f32_e32 v22, v154, v21
	v_cvt_pk_bf16_f32 v185, v5, v21
	v_fma_f32 v6, -v155, v21, v6
	v_fmac_f32_e32 v22, v155, v5
	ds_write_b32 v172, v185 offset:61232
	s_waitcnt lgkmcnt(4)
	v_mfma_f32_16x16x32_bf16 v[232:235], v[82:85], v[216:219], 0
	v_fmac_f32_e32 v7, v154, v6
	v_fmac_f32_e32 v23, v154, v22
	v_cvt_pk_bf16_f32 v184, v6, v22
	v_fma_f32 v7, -v155, v22, v7
	v_fmac_f32_e32 v23, v155, v6
	ds_write_b32 v172, v184 offset:61504
	v_mfma_f32_16x16x32_bf16 v[232:235], v[86:89], v[220:223], v[232:235]
	v_fmac_f32_e32 v8, v154, v7
	v_fmac_f32_e32 v24, v154, v23
	v_cvt_pk_bf16_f32 v185, v7, v23
	v_fma_f32 v8, -v155, v23, v8
	v_fmac_f32_e32 v24, v155, v7
	ds_write_b32 v172, v185 offset:61776
	v_mfma_f32_16x16x32_bf16 v[232:235], v[90:93], v[224:227], v[232:235]
	v_fmac_f32_e32 v9, v154, v8
	v_fmac_f32_e32 v25, v154, v24
	v_cvt_pk_bf16_f32 v184, v8, v24
	v_fma_f32 v9, -v155, v24, v9
	v_fmac_f32_e32 v25, v155, v8
	ds_write_b32 v172, v184 offset:62048
	v_mfma_f32_16x16x32_bf16 v[232:235], v[94:97], v[228:231], v[232:235]
	v_fmac_f32_e32 v10, v154, v9
	v_fmac_f32_e32 v26, v154, v25
	v_cvt_pk_bf16_f32 v185, v9, v25
	v_fma_f32 v10, -v155, v25, v10
	v_fmac_f32_e32 v26, v155, v9
	ds_write_b32 v172, v185 offset:62320
	v_fmac_f32_e32 v11, v154, v10
	v_fmac_f32_e32 v27, v154, v26
	v_cvt_pk_bf16_f32 v184, v10, v26
	v_fma_f32 v11, -v155, v26, v11
	v_fmac_f32_e32 v27, v155, v10
	ds_write_b32 v172, v184 offset:62592
	v_fmac_f32_e32 v12, v154, v11
	v_fmac_f32_e32 v28, v154, v27
	v_cvt_pk_bf16_f32 v185, v11, v27
	v_fma_f32 v12, -v155, v27, v12
	v_fmac_f32_e32 v28, v155, v11
	ds_write_b32 v172, v185 offset:62864
	s_cmp_lt_u32 s28, 2
	s_cbranch_scc1 .LS5Q_nstr1d0j1
	global_store_dwordx4 v[240:241], v[232:235], off
	v_lshl_add_u64 v[240:241], v[240:241], 0, s[50:51]
.LS5Q_nstr1d0j1:
	v_fmac_f32_e32 v13, v154, v12
	v_fmac_f32_e32 v29, v154, v28
	v_cvt_pk_bf16_f32 v184, v12, v28
	v_fma_f32 v13, -v155, v28, v13
	v_fmac_f32_e32 v29, v155, v12
	ds_write_b32 v172, v184 offset:63136
	v_fmac_f32_e32 v14, v154, v13
	v_fmac_f32_e32 v30, v154, v29
	v_cvt_pk_bf16_f32 v185, v13, v29
	v_fma_f32 v14, -v155, v29, v14
	v_fmac_f32_e32 v30, v155, v13
	ds_write_b32 v172, v185 offset:63408
	v_fmac_f32_e32 v15, v154, v14
	v_fmac_f32_e32 v31, v154, v30
	v_cvt_pk_bf16_f32 v184, v14, v30
	v_fma_f32 v15, -v155, v30, v15
	v_fmac_f32_e32 v31, v155, v14
	ds_write_b32 v172, v184 offset:63680
	v_fmac_f32_e32 v16, v154, v15
	v_fmac_f32_e32 v32, v154, v31
	v_cvt_pk_bf16_f32 v185, v15, v31
	v_fma_f32 v16, -v155, v31, v16
	v_fmac_f32_e32 v32, v155, v15
	ds_write_b32 v172, v185 offset:63952
	v_fma_f32 v180, v154, v16, v17
	v_fma_f32 v176, v154, v32, v33
	v_cvt_pk_bf16_f32 v184, v16, v32
	v_fma_f32 v180, -v155, v32, v180
	v_fmac_f32_e32 v176, v155, v16
	ds_write_b32 v172, v184 offset:64224
	v_cvt_pk_bf16_f32 v185, v180, v176
	ds_write_b32 v172, v185 offset:64496
	s_waitcnt lgkmcnt(0)
	s_barrier
	s_add_u32 s28, s28, 1
	s_cmp_lt_u32 s28, 4
	s_cbranch_scc0 .LS5Q_wr1d0j2
	s_waitcnt vmcnt(2)
.LS5Q_wr1d0j2:
	s_waitcnt vmcnt(4)
	v_cvt_pk_bf16_f32 v212, v102, v103
	v_cvt_pk_bf16_f32 v213, v104, v105
	v_cvt_pk_bf16_f32 v214, v98, v99
	v_cvt_pk_bf16_f32 v215, v100, v101
	s_add_u32 s20, s28, 3
	s_cmp_lt_u32 s20, s52
	s_cselect_b64 s[58:59], s[50:51], 0
	v_lshl_add_u64 v[248:249], v[248:249], 0, s[58:59]
	global_load_dwordx4 v[98:101], v[248:249], off offset:16
	global_load_dwordx4 v[102:105], v[248:249], off
	ds_read_b128 v[216:219], v173 offset:0
	ds_read_b128 v[220:223], v173 offset:64
	ds_read_b128 v[224:227], v173 offset:128
	ds_read_b128 v[228:231], v173 offset:192
	v_fmac_f32_e32 v34, v154, v180
	v_fmac_f32_e32 v50, v154, v176
	v_fma_f32 v34, -v155, v176, v34
	v_fmac_f32_e32 v50, v155, v180
	v_mfma_f32_32x32x16_bf16 v[2:17], v[212:215], v[70:73], 0
	v_fmac_f32_e32 v35, v154, v34
	v_fmac_f32_e32 v51, v154, v50
	v_cvt_pk_bf16_f32 v184, v34, v50
	v_fma_f32 v35, -v155, v50, v35
	v_fmac_f32_e32 v51, v155, v34
	ds_write_b32 v174, v184 offset:0
	v_fmac_f32_e32 v36, v154, v35
	v_fmac_f32_e32 v52, v154, v51
	v_cvt_pk_bf16_f32 v185, v35, v51
	v_fma_f32 v36, -v155, v51, v36
	v_fmac_f32_e32 v52, v155, v35
	ds_write_b32 v174, v185 offset:272
	v_mfma_f32_32x32x16_bf16 v[18:33], v[212:215], v[78:81], 0
	v_fmac_f32_e32 v37, v154, v36
	v_fmac_f32_e32 v53, v154, v52
	v_cvt_pk_bf16_f32 v184, v36, v52
	v_fma_f32 v37, -v155, v52, v37
	v_fmac_f32_e32 v53, v155, v36
	ds_write_b32 v174, v184 offset:544
	v_fmac_f32_e32 v38, v154, v37
	v_fmac_f32_e32 v54, v154, v53
	v_cvt_pk_bf16_f32 v185, v37, v53
	v_fma_f32 v38, -v155, v53, v38
	v_fmac_f32_e32 v54, v155, v37
	ds_write_b32 v174, v185 offset:816
	s_waitcnt lgkmcnt(4)
	v_mfma_f32_16x16x32_bf16 v[232:235], v[82:85], v[216:219], 0
	v_fmac_f32_e32 v39, v154, v38
	v_fmac_f32_e32 v55, v154, v54
	v_cvt_pk_bf16_f32 v184, v38, v54
	v_fma_f32 v39, -v155, v54, v39
	v_fmac_f32_e32 v55, v155, v38
	ds_write_b32 v174, v184 offset:1088
	v_mfma_f32_16x16x32_bf16 v[232:235], v[86:89], v[220:223], v[232:235]
	v_fmac_f32_e32 v40, v154, v39
	v_fmac_f32_e32 v56, v154, v55
	v_cvt_pk_bf16_f32 v185, v39, v55
	v_fma_f32 v40, -v155, v55, v40
	v_fmac_f32_e32 v56, v155, v39
	ds_write_b32 v174, v185 offset:1360
	v_mfma_f32_16x16x32_bf16 v[232:235], v[90:93], v[224:227], v[232:235]
	v_fmac_f32_e32 v41, v154, v40
	v_fmac_f32_e32 v57, v154, v56
	v_cvt_pk_bf16_f32 v184, v40, v56
	v_fma_f32 v41, -v155, v56, v41
	v_fmac_f32_e32 v57, v155, v40
	ds_write_b32 v174, v184 offset:1632
	v_mfma_f32_16x16x32_bf16 v[232:235], v[94:97], v[228:231], v[232:235]
	v_fmac_f32_e32 v42, v154, v41
	v_fmac_f32_e32 v58, v154, v57
	v_cvt_pk_bf16_f32 v185, v41, v57
	v_fma_f32 v42, -v155, v57, v42
	v_fmac_f32_e32 v58, v155, v41
	ds_write_b32 v174, v185 offset:1904
	v_fmac_f32_e32 v43, v154, v42
	v_fmac_f32_e32 v59, v154, v58
	v_cvt_pk_bf16_f32 v184, v42, v58
	v_fma_f32 v43, -v155, v58, v43
	v_fmac_f32_e32 v59, v155, v42
	ds_write_b32 v174, v184 offset:2176
	v_fmac_f32_e32 v44, v154, v43
	v_fmac_f32_e32 v60, v154, v59
	v_cvt_pk_bf16_f32 v185, v43, v59
	v_fma_f32 v44, -v155, v59, v44
	v_fmac_f32_e32 v60, v155, v43
	ds_write_b32 v174, v185 offset:2448
	global_store_dwordx4 v[240:241], v[232:235], off
	v_lshl_add_u64 v[240:241], v[240:241], 0, s[50:51]
	v_fmac_f32_e32 v45, v154, v44
	v_fmac_f32_e32 v61, v154, v60
	v_cvt_pk_bf16_f32 v184, v44, v60
	v_fma_f32 v45, -v155, v60, v45
	v_fmac_f32_e32 v61, v155, v44
	ds_write_b32 v174, v184 offset:2720
	v_fmac_f32_e32 v46, v154, v45
	v_fmac_f32_e32 v62, v154, v61
	v_cvt_pk_bf16_f32 v185, v45, v61
	v_fma_f32 v46, -v155, v61, v46
	v_fmac_f32_e32 v62, v155, v45
	ds_write_b32 v174, v185 offset:2992
	v_fmac_f32_e32 v47, v154, v46
	v_fmac_f32_e32 v63, v154, v62
	v_cvt_pk_bf16_f32 v184, v46, v62
	v_fma_f32 v47, -v155, v62, v47
	v_fmac_f32_e32 v63, v155, v46
	ds_write_b32 v174, v184 offset:3264
	v_fmac_f32_e32 v48, v154, v47
	v_fmac_f32_e32 v64, v154, v63
	v_cvt_pk_bf16_f32 v185, v47, v63
	v_fma_f32 v48, -v155, v63, v48
	v_fmac_f32_e32 v64, v155, v47
	ds_write_b32 v174, v185 offset:3536
	v_fma_f32 v180, v154, v48, v49
	v_fma_f32 v176, v154, v64, v65
	v_cvt_pk_bf16_f32 v184, v48, v64
	v_fma_f32 v180, -v155, v64, v180
	v_fmac_f32_e32 v176, v155, v48
	ds_write_b32 v174, v184 offset:3808
	v_cvt_pk_bf16_f32 v185, v180, v176
	ds_write_b32 v174, v185 offset:4080
	s_add_u32 s28, s28, 1
	s_cmp_lt_u32 s28, 4
	s_cbranch_scc0 .LS5Q_wr1d0j3
	s_waitcnt vmcnt(2)
.LS5Q_wr1d0j3:
	s_waitcnt vmcnt(4)
	v_cvt_pk_bf16_f32 v212, v106, v107
	v_cvt_pk_bf16_f32 v213, v108, v109
	v_cvt_pk_bf16_f32 v214, v110, v111
	v_cvt_pk_bf16_f32 v215, v112, v113
	s_add_u32 s20, s28, 3
	s_cmp_lt_u32 s20, s52
	s_cselect_b64 s[58:59], s[50:51], 0
	v_lshl_add_u64 v[248:249], v[248:249], 0, s[58:59]
	global_load_dwordx4 v[110:113], v[248:249], off offset:16
	global_load_dwordx4 v[106:109], v[248:249], off
	ds_read_b128 v[216:219], v173 offset:60416
	ds_read_b128 v[220:223], v173 offset:60480
	ds_read_b128 v[224:227], v173 offset:60544
	ds_read_b128 v[228:231], v173 offset:60608
	v_fmac_f32_e32 v2, v154, v180
	v_fmac_f32_e32 v18, v154, v176
	v_fma_f32 v2, -v155, v176, v2
	v_fmac_f32_e32 v18, v155, v180
	v_mfma_f32_32x32x16_bf16 v[34:49], v[212:215], v[70:73], 0
	v_fmac_f32_e32 v3, v154, v2
	v_fmac_f32_e32 v19, v154, v18
	v_cvt_pk_bf16_f32 v184, v2, v18
	v_fma_f32 v3, -v155, v18, v3
	v_fmac_f32_e32 v19, v155, v2
	ds_write_b32 v174, v184 offset:60416
	v_fmac_f32_e32 v4, v154, v3
	v_fmac_f32_e32 v20, v154, v19
	v_cvt_pk_bf16_f32 v185, v3, v19
	v_fma_f32 v4, -v155, v19, v4
	v_fmac_f32_e32 v20, v155, v3
	ds_write_b32 v174, v185 offset:60688
	v_mfma_f32_32x32x16_bf16 v[50:65], v[212:215], v[78:81], 0
	v_fmac_f32_e32 v5, v154, v4
	v_fmac_f32_e32 v21, v154, v20
	v_cvt_pk_bf16_f32 v184, v4, v20
	v_fma_f32 v5, -v155, v20, v5
	v_fmac_f32_e32 v21, v155, v4
	ds_write_b32 v174, v184 offset:60960
	v_fmac_f32_e32 v6, v154, v5
	v_fmac_f32_e32 v22, v154, v21
	v_cvt_pk_bf16_f32 v185, v5, v21
	v_fma_f32 v6, -v155, v21, v6
	v_fmac_f32_e32 v22, v155, v5
	ds_write_b32 v174, v185 offset:61232
	s_waitcnt lgkmcnt(4)
	v_mfma_f32_16x16x32_bf16 v[232:235], v[82:85], v[216:219], 0
	v_fmac_f32_e32 v7, v154, v6
	v_fmac_f32_e32 v23, v154, v22
	v_cvt_pk_bf16_f32 v184, v6, v22
	v_fma_f32 v7, -v155, v22, v7
	v_fmac_f32_e32 v23, v155, v6
	ds_write_b32 v174, v184 offset:61504
	v_mfma_f32_16x16x32_bf16 v[232:235], v[86:89], v[220:223], v[232:235]
	v_fmac_f32_e32 v8, v154, v7
	v_fmac_f32_e32 v24, v154, v23
	v_cvt_pk_bf16_f32 v185, v7, v23
	v_fma_f32 v8, -v155, v23, v8
	v_fmac_f32_e32 v24, v155, v7
	ds_write_b32 v174, v185 offset:61776
	v_mfma_f32_16x16x32_bf16 v[232:235], v[90:93], v[224:227], v[232:235]
	v_fmac_f32_e32 v9, v154, v8
	v_fmac_f32_e32 v25, v154, v24
	v_cvt_pk_bf16_f32 v184, v8, v24
	v_fma_f32 v9, -v155, v24, v9
	v_fmac_f32_e32 v25, v155, v8
	ds_write_b32 v174, v184 offset:62048
	v_mfma_f32_16x16x32_bf16 v[232:235], v[94:97], v[228:231], v[232:235]
	v_fmac_f32_e32 v10, v154, v9
	v_fmac_f32_e32 v26, v154, v25
	v_cvt_pk_bf16_f32 v185, v9, v25
	v_fma_f32 v10, -v155, v25, v10
	v_fmac_f32_e32 v26, v155, v9
	ds_write_b32 v174, v185 offset:62320
	v_fmac_f32_e32 v11, v154, v10
	v_fmac_f32_e32 v27, v154, v26
	v_cvt_pk_bf16_f32 v184, v10, v26
	v_fma_f32 v11, -v155, v26, v11
	v_fmac_f32_e32 v27, v155, v10
	ds_write_b32 v174, v184 offset:62592
	v_fmac_f32_e32 v12, v154, v11
	v_fmac_f32_e32 v28, v154, v27
	v_cvt_pk_bf16_f32 v185, v11, v27
	v_fma_f32 v12, -v155, v27, v12
	v_fmac_f32_e32 v28, v155, v11
	ds_write_b32 v174, v185 offset:62864
	global_store_dwordx4 v[240:241], v[232:235], off
	v_lshl_add_u64 v[240:241], v[240:241], 0, s[50:51]
	v_fmac_f32_e32 v13, v154, v12
	v_fmac_f32_e32 v29, v154, v28
	v_cvt_pk_bf16_f32 v184, v12, v28
	v_fma_f32 v13, -v155, v28, v13
	v_fmac_f32_e32 v29, v155, v12
	ds_write_b32 v174, v184 offset:63136
	v_fmac_f32_e32 v14, v154, v13
	v_fmac_f32_e32 v30, v154, v29
	v_cvt_pk_bf16_f32 v185, v13, v29
	v_fma_f32 v14, -v155, v29, v14
	v_fmac_f32_e32 v30, v155, v13
	ds_write_b32 v174, v185 offset:63408
	v_fmac_f32_e32 v15, v154, v14
	v_fmac_f32_e32 v31, v154, v30
	v_cvt_pk_bf16_f32 v184, v14, v30
	v_fma_f32 v15, -v155, v30, v15
	v_fmac_f32_e32 v31, v155, v14
	ds_write_b32 v174, v184 offset:63680
	v_fmac_f32_e32 v16, v154, v15
	v_fmac_f32_e32 v32, v154, v31
	v_cvt_pk_bf16_f32 v185, v15, v31
	v_fma_f32 v16, -v155, v31, v16
	v_fmac_f32_e32 v32, v155, v15
	ds_write_b32 v174, v185 offset:63952
	v_fma_f32 v180, v154, v16, v17
	v_fma_f32 v176, v154, v32, v33
	v_cvt_pk_bf16_f32 v184, v16, v32
	v_fma_f32 v180, -v155, v32, v180
	v_fmac_f32_e32 v176, v155, v16
	ds_write_b32 v174, v184 offset:64224
	v_cvt_pk_bf16_f32 v185, v180, v176
	ds_write_b32 v174, v185 offset:64496
	s_waitcnt lgkmcnt(0)
	s_barrier
	s_add_u32 s28, s28, 1
	s_cmp_lt_u32 s28, s52
	s_cbranch_scc1 .LS5Q_loopr1d0
	s_branch .LS5Q_epi

.LS5Q_wr0d1j0:
	s_waitcnt vmcnt(4)
	v_cvt_pk_bf16_f32 v212, v102, v103
	v_cvt_pk_bf16_f32 v213, v104, v105
	v_cvt_pk_bf16_f32 v214, v98, v99
	v_cvt_pk_bf16_f32 v215, v100, v101
	s_add_u32 s20, s28, 3
	s_cmp_lt_u32 s20, s52
	s_cselect_b64 s[58:59], s[50:51], 0
	v_lshl_add_u64 v[248:249], v[248:249], 0, s[58:59]
	global_load_dwordx4 v[98:101], v[248:249], off offset:16
	global_load_dwordx4 v[102:105], v[248:249], off
	ds_read_b128 v[216:219], v175 offset:0
	ds_read_b128 v[220:223], v175 offset:64
	ds_read_b128 v[224:227], v175 offset:128
	ds_read_b128 v[228:231], v175 offset:192
	v_fmac_f32_e32 v49, v152, v182
	v_fmac_f32_e32 v65, v152, v178
	v_fma_f32 v49, -v153, v178, v49
	v_fmac_f32_e32 v65, v153, v182
	v_mfma_f32_32x32x16_bf16 v[2:17], v[212:215], v[66:69], 0
	v_fmac_f32_e32 v48, v152, v49
	v_fmac_f32_e32 v64, v152, v65
	v_cvt_pk_bf16_f32 v184, v49, v65
	v_fma_f32 v48, -v153, v65, v48
	v_fmac_f32_e32 v64, v153, v49
	ds_write_b32 v172, v184 offset:4080
	v_fmac_f32_e32 v47, v152, v48
	v_fmac_f32_e32 v63, v152, v64
	v_cvt_pk_bf16_f32 v185, v48, v64
	v_fma_f32 v47, -v153, v64, v47
	v_fmac_f32_e32 v63, v153, v48
	ds_write_b32 v172, v185 offset:3808
	v_mfma_f32_32x32x16_bf16 v[18:33], v[212:215], v[74:77], 0
	v_fmac_f32_e32 v46, v152, v47
	v_fmac_f32_e32 v62, v152, v63
	v_cvt_pk_bf16_f32 v184, v47, v63
	v_fma_f32 v46, -v153, v63, v46
	v_fmac_f32_e32 v62, v153, v47
	ds_write_b32 v172, v184 offset:3536
	v_fmac_f32_e32 v45, v152, v46
	v_fmac_f32_e32 v61, v152, v62
	v_cvt_pk_bf16_f32 v185, v46, v62
	v_fma_f32 v45, -v153, v62, v45
	v_fmac_f32_e32 v61, v153, v46
	ds_write_b32 v172, v185 offset:3264
	s_waitcnt lgkmcnt(4)
	v_mfma_f32_16x16x32_bf16 v[232:235], v[82:85], v[216:219], 0
	v_fmac_f32_e32 v44, v152, v45
	v_fmac_f32_e32 v60, v152, v61
	v_cvt_pk_bf16_f32 v184, v45, v61
	v_fma_f32 v44, -v153, v61, v44
	v_fmac_f32_e32 v60, v153, v45
	ds_write_b32 v172, v184 offset:2992
	v_mfma_f32_16x16x32_bf16 v[232:235], v[86:89], v[220:223], v[232:235]
	v_fmac_f32_e32 v43, v152, v44
	v_fmac_f32_e32 v59, v152, v60
	v_cvt_pk_bf16_f32 v185, v44, v60
	v_fma_f32 v43, -v153, v60, v43
	v_fmac_f32_e32 v59, v153, v44
	ds_write_b32 v172, v185 offset:2720
	v_mfma_f32_16x16x32_bf16 v[232:235], v[90:93], v[224:227], v[232:235]
	v_fmac_f32_e32 v42, v152, v43
	v_fmac_f32_e32 v58, v152, v59
	v_cvt_pk_bf16_f32 v184, v43, v59
	v_fma_f32 v42, -v153, v59, v42
	v_fmac_f32_e32 v58, v153, v43
	ds_write_b32 v172, v184 offset:2448
	v_mfma_f32_16x16x32_bf16 v[232:235], v[94:97], v[228:231], v[232:235]
	v_fmac_f32_e32 v41, v152, v42
	v_fmac_f32_e32 v57, v152, v58
	v_cvt_pk_bf16_f32 v185, v42, v58
	v_fma_f32 v41, -v153, v58, v41
	v_fmac_f32_e32 v57, v153, v42
	ds_write_b32 v172, v185 offset:2176
	v_fmac_f32_e32 v40, v152, v41
	v_fmac_f32_e32 v56, v152, v57
	v_cvt_pk_bf16_f32 v184, v41, v57
	v_fma_f32 v40, -v153, v57, v40
	v_fmac_f32_e32 v56, v153, v41
	ds_write_b32 v172, v184 offset:1904
	v_fmac_f32_e32 v39, v152, v40
	v_fmac_f32_e32 v55, v152, v56
	v_cvt_pk_bf16_f32 v185, v40, v56
	v_fma_f32 v39, -v153, v56, v39
	v_fmac_f32_e32 v55, v153, v40
	ds_write_b32 v172, v185 offset:1632
	s_cmp_lt_u32 s28, 2
	s_cbranch_scc1 .LS5Q_nstr0d1j0
	global_store_dwordx4 v[240:241], v[232:235], off
	v_lshl_add_u64 v[240:241], v[240:241], 0, s[50:51]
.LS5Q_nstr0d1j0:
	v_fmac_f32_e32 v38, v152, v39
	v_fmac_f32_e32 v54, v152, v55
	v_cvt_pk_bf16_f32 v184, v39, v55
	v_fma_f32 v38, -v153, v55, v38
	v_fmac_f32_e32 v54, v153, v39
	ds_write_b32 v172, v184 offset:1360
	v_fmac_f32_e32 v37, v152, v38
	v_fmac_f32_e32 v53, v152, v54
	v_cvt_pk_bf16_f32 v185, v38, v54
	v_fma_f32 v37, -v153, v54, v37
	v_fmac_f32_e32 v53, v153, v38
	ds_write_b32 v172, v185 offset:1088
	v_fmac_f32_e32 v36, v152, v37
	v_fmac_f32_e32 v52, v152, v53
	v_cvt_pk_bf16_f32 v184, v37, v53
	v_fma_f32 v36, -v153, v53, v36
	v_fmac_f32_e32 v52, v153, v37
	ds_write_b32 v172, v184 offset:816
	v_fmac_f32_e32 v35, v152, v36
	v_fmac_f32_e32 v51, v152, v52
	v_cvt_pk_bf16_f32 v185, v36, v52
	v_fma_f32 v35, -v153, v52, v35
	v_fmac_f32_e32 v51, v153, v36
	ds_write_b32 v172, v185 offset:544
	v_fma_f32 v182, v152, v35, v34
	v_fma_f32 v178, v152, v51, v50
	v_cvt_pk_bf16_f32 v184, v35, v51
	v_fma_f32 v182, -v153, v51, v182
	v_fmac_f32_e32 v178, v153, v35
	ds_write_b32 v172, v184 offset:272
	v_cvt_pk_bf16_f32 v185, v182, v178
	ds_write_b32 v172, v185 offset:0
	s_add_u32 s28, s28, 1
	s_cmp_lt_u32 s28, 4
	s_cbranch_scc0 .LS5Q_wr0d1j1
	s_waitcnt vmcnt(2)
.LS5Q_wr0d1j1:
	s_waitcnt vmcnt(4)
	v_cvt_pk_bf16_f32 v212, v106, v107
	v_cvt_pk_bf16_f32 v213, v108, v109
	v_cvt_pk_bf16_f32 v214, v110, v111
	v_cvt_pk_bf16_f32 v215, v112, v113
	s_add_u32 s20, s28, 3
	s_cmp_lt_u32 s20, s52
	s_cselect_b64 s[58:59], s[50:51], 0
	v_lshl_add_u64 v[248:249], v[248:249], 0, s[58:59]
	global_load_dwordx4 v[110:113], v[248:249], off offset:16
	global_load_dwordx4 v[106:109], v[248:249], off
	ds_read_b128 v[216:219], v175 offset:60416
	ds_read_b128 v[220:223], v175 offset:60480
	ds_read_b128 v[224:227], v175 offset:60544
	ds_read_b128 v[228:231], v175 offset:60608
	v_fmac_f32_e32 v17, v152, v182
	v_fmac_f32_e32 v33, v152, v178
	v_fma_f32 v17, -v153, v178, v17
	v_fmac_f32_e32 v33, v153, v182
	v_mfma_f32_32x32x16_bf16 v[34:49], v[212:215], v[66:69], 0
	v_fmac_f32_e32 v16, v152, v17
	v_fmac_f32_e32 v32, v152, v33
	v_cvt_pk_bf16_f32 v184, v17, v33
	v_fma_f32 v16, -v153, v33, v16
	v_fmac_f32_e32 v32, v153, v17
	ds_write_b32 v172, v184 offset:64496
	v_fmac_f32_e32 v15, v152, v16
	v_fmac_f32_e32 v31, v152, v32
	v_cvt_pk_bf16_f32 v185, v16, v32
	v_fma_f32 v15, -v153, v32, v15
	v_fmac_f32_e32 v31, v153, v16
	ds_write_b32 v172, v185 offset:64224
	v_mfma_f32_32x32x16_bf16 v[50:65], v[212:215], v[74:77], 0
	v_fmac_f32_e32 v14, v152, v15
	v_fmac_f32_e32 v30, v152, v31
	v_cvt_pk_bf16_f32 v184, v15, v31
	v_fma_f32 v14, -v153, v31, v14
	v_fmac_f32_e32 v30, v153, v15
	ds_write_b32 v172, v184 offset:63952
	v_fmac_f32_e32 v13, v152, v14
	v_fmac_f32_e32 v29, v152, v30
	v_cvt_pk_bf16_f32 v185, v14, v30
	v_fma_f32 v13, -v153, v30, v13
	v_fmac_f32_e32 v29, v153, v14
	ds_write_b32 v172, v185 offset:63680
	s_waitcnt lgkmcnt(4)
	v_mfma_f32_16x16x32_bf16 v[232:235], v[82:85], v[216:219], 0
	v_fmac_f32_e32 v12, v152, v13
	v_fmac_f32_e32 v28, v152, v29
	v_cvt_pk_bf16_f32 v184, v13, v29
	v_fma_f32 v12, -v153, v29, v12
	v_fmac_f32_e32 v28, v153, v13
	ds_write_b32 v172, v184 offset:63408
	v_mfma_f32_16x16x32_bf16 v[232:235], v[86:89], v[220:223], v[232:235]
	v_fmac_f32_e32 v11, v152, v12
	v_fmac_f32_e32 v27, v152, v28
	v_cvt_pk_bf16_f32 v185, v12, v28
	v_fma_f32 v11, -v153, v28, v11
	v_fmac_f32_e32 v27, v153, v12
	ds_write_b32 v172, v185 offset:63136
	v_mfma_f32_16x16x32_bf16 v[232:235], v[90:93], v[224:227], v[232:235]
	v_fmac_f32_e32 v10, v152, v11
	v_fmac_f32_e32 v26, v152, v27
	v_cvt_pk_bf16_f32 v184, v11, v27
	v_fma_f32 v10, -v153, v27, v10
	v_fmac_f32_e32 v26, v153, v11
	ds_write_b32 v172, v184 offset:62864
	v_mfma_f32_16x16x32_bf16 v[232:235], v[94:97], v[228:231], v[232:235]
	v_fmac_f32_e32 v9, v152, v10
	v_fmac_f32_e32 v25, v152, v26
	v_cvt_pk_bf16_f32 v185, v10, v26
	v_fma_f32 v9, -v153, v26, v9
	v_fmac_f32_e32 v25, v153, v10
	ds_write_b32 v172, v185 offset:62592
	v_fmac_f32_e32 v8, v152, v9
	v_fmac_f32_e32 v24, v152, v25
	v_cvt_pk_bf16_f32 v184, v9, v25
	v_fma_f32 v8, -v153, v25, v8
	v_fmac_f32_e32 v24, v153, v9
	ds_write_b32 v172, v184 offset:62320
	v_fmac_f32_e32 v7, v152, v8
	v_fmac_f32_e32 v23, v152, v24
	v_cvt_pk_bf16_f32 v185, v8, v24
	v_fma_f32 v7, -v153, v24, v7
	v_fmac_f32_e32 v23, v153, v8
	ds_write_b32 v172, v185 offset:62048
	s_cmp_lt_u32 s28, 2
	s_cbranch_scc1 .LS5Q_nstr0d1j1
	global_store_dwordx4 v[240:241], v[232:235], off
	v_lshl_add_u64 v[240:241], v[240:241], 0, s[50:51]
.LS5Q_nstr0d1j1:
	v_fmac_f32_e32 v6, v152, v7
	v_fmac_f32_e32 v22, v152, v23
	v_cvt_pk_bf16_f32 v184, v7, v23
	v_fma_f32 v6, -v153, v23, v6
	v_fmac_f32_e32 v22, v153, v7
	ds_write_b32 v172, v184 offset:61776
	v_fmac_f32_e32 v5, v152, v6
	v_fmac_f32_e32 v21, v152, v22
	v_cvt_pk_bf16_f32 v185, v6, v22
	v_fma_f32 v5, -v153, v22, v5
	v_fmac_f32_e32 v21, v153, v6
	ds_write_b32 v172, v185 offset:61504
	v_fmac_f32_e32 v4, v152, v5
	v_fmac_f32_e32 v20, v152, v21
	v_cvt_pk_bf16_f32 v184, v5, v21
	v_fma_f32 v4, -v153, v21, v4
	v_fmac_f32_e32 v20, v153, v5
	ds_write_b32 v172, v184 offset:61232
	v_fmac_f32_e32 v3, v152, v4
	v_fmac_f32_e32 v19, v152, v20
	v_cvt_pk_bf16_f32 v185, v4, v20
	v_fma_f32 v3, -v153, v20, v3
	v_fmac_f32_e32 v19, v153, v4
	ds_write_b32 v172, v185 offset:60960
	v_fma_f32 v182, v152, v3, v2
	v_fma_f32 v178, v152, v19, v18
	v_cvt_pk_bf16_f32 v184, v3, v19
	v_fma_f32 v182, -v153, v19, v182
	v_fmac_f32_e32 v178, v153, v3
	ds_write_b32 v172, v184 offset:60688
	v_cvt_pk_bf16_f32 v185, v182, v178
	ds_write_b32 v172, v185 offset:60416
	s_waitcnt lgkmcnt(0)
	s_barrier
	s_add_u32 s28, s28, 1
	s_cmp_lt_u32 s28, 4
	s_cbranch_scc0 .LS5Q_wr0d1j2
	s_waitcnt vmcnt(2)
.LS5Q_wr0d1j2:
	s_waitcnt vmcnt(4)
	v_cvt_pk_bf16_f32 v212, v102, v103
	v_cvt_pk_bf16_f32 v213, v104, v105
	v_cvt_pk_bf16_f32 v214, v98, v99
	v_cvt_pk_bf16_f32 v215, v100, v101
	s_add_u32 s20, s28, 3
	s_cmp_lt_u32 s20, s52
	s_cselect_b64 s[58:59], s[50:51], 0
	v_lshl_add_u64 v[248:249], v[248:249], 0, s[58:59]
	global_load_dwordx4 v[98:101], v[248:249], off offset:16
	global_load_dwordx4 v[102:105], v[248:249], off
	ds_read_b128 v[216:219], v173 offset:0
	ds_read_b128 v[220:223], v173 offset:64
	ds_read_b128 v[224:227], v173 offset:128
	ds_read_b128 v[228:231], v173 offset:192
	v_fmac_f32_e32 v49, v152, v182
	v_fmac_f32_e32 v65, v152, v178
	v_fma_f32 v49, -v153, v178, v49
	v_fmac_f32_e32 v65, v153, v182
	v_mfma_f32_32x32x16_bf16 v[2:17], v[212:215], v[66:69], 0
	v_fmac_f32_e32 v48, v152, v49
	v_fmac_f32_e32 v64, v152, v65
	v_cvt_pk_bf16_f32 v184, v49, v65
	v_fma_f32 v48, -v153, v65, v48
	v_fmac_f32_e32 v64, v153, v49
	ds_write_b32 v174, v184 offset:4080
	v_fmac_f32_e32 v47, v152, v48
	v_fmac_f32_e32 v63, v152, v64
	v_cvt_pk_bf16_f32 v185, v48, v64
	v_fma_f32 v47, -v153, v64, v47
	v_fmac_f32_e32 v63, v153, v48
	ds_write_b32 v174, v185 offset:3808
	v_mfma_f32_32x32x16_bf16 v[18:33], v[212:215], v[74:77], 0
	v_fmac_f32_e32 v46, v152, v47
	v_fmac_f32_e32 v62, v152, v63
	v_cvt_pk_bf16_f32 v184, v47, v63
	v_fma_f32 v46, -v153, v63, v46
	v_fmac_f32_e32 v62, v153, v47
	ds_write_b32 v174, v184 offset:3536
	v_fmac_f32_e32 v45, v152, v46
	v_fmac_f32_e32 v61, v152, v62
	v_cvt_pk_bf16_f32 v185, v46, v62
	v_fma_f32 v45, -v153, v62, v45
	v_fmac_f32_e32 v61, v153, v46
	ds_write_b32 v174, v185 offset:3264
	s_waitcnt lgkmcnt(4)
	v_mfma_f32_16x16x32_bf16 v[232:235], v[82:85], v[216:219], 0
	v_fmac_f32_e32 v44, v152, v45
	v_fmac_f32_e32 v60, v152, v61
	v_cvt_pk_bf16_f32 v184, v45, v61
	v_fma_f32 v44, -v153, v61, v44
	v_fmac_f32_e32 v60, v153, v45
	ds_write_b32 v174, v184 offset:2992
	v_mfma_f32_16x16x32_bf16 v[232:235], v[86:89], v[220:223], v[232:235]
	v_fmac_f32_e32 v43, v152, v44
	v_fmac_f32_e32 v59, v152, v60
	v_cvt_pk_bf16_f32 v185, v44, v60
	v_fma_f32 v43, -v153, v60, v43
	v_fmac_f32_e32 v59, v153, v44
	ds_write_b32 v174, v185 offset:2720
	v_mfma_f32_16x16x32_bf16 v[232:235], v[90:93], v[224:227], v[232:235]
	v_fmac_f32_e32 v42, v152, v43
	v_fmac_f32_e32 v58, v152, v59
	v_cvt_pk_bf16_f32 v184, v43, v59
	v_fma_f32 v42, -v153, v59, v42
	v_fmac_f32_e32 v58, v153, v43
	ds_write_b32 v174, v184 offset:2448
	v_mfma_f32_16x16x32_bf16 v[232:235], v[94:97], v[228:231], v[232:235]
	v_fmac_f32_e32 v41, v152, v42
	v_fmac_f32_e32 v57, v152, v58
	v_cvt_pk_bf16_f32 v185, v42, v58
	v_fma_f32 v41, -v153, v58, v41
	v_fmac_f32_e32 v57, v153, v42
	ds_write_b32 v174, v185 offset:2176
	v_fmac_f32_e32 v40, v152, v41
	v_fmac_f32_e32 v56, v152, v57
	v_cvt_pk_bf16_f32 v184, v41, v57
	v_fma_f32 v40, -v153, v57, v40
	v_fmac_f32_e32 v56, v153, v41
	ds_write_b32 v174, v184 offset:1904
	v_fmac_f32_e32 v39, v152, v40
	v_fmac_f32_e32 v55, v152, v56
	v_cvt_pk_bf16_f32 v185, v40, v56
	v_fma_f32 v39, -v153, v56, v39
	v_fmac_f32_e32 v55, v153, v40
	ds_write_b32 v174, v185 offset:1632
	global_store_dwordx4 v[240:241], v[232:235], off
	v_lshl_add_u64 v[240:241], v[240:241], 0, s[50:51]
	v_fmac_f32_e32 v38, v152, v39
	v_fmac_f32_e32 v54, v152, v55
	v_cvt_pk_bf16_f32 v184, v39, v55
	v_fma_f32 v38, -v153, v55, v38
	v_fmac_f32_e32 v54, v153, v39
	ds_write_b32 v174, v184 offset:1360
	v_fmac_f32_e32 v37, v152, v38
	v_fmac_f32_e32 v53, v152, v54
	v_cvt_pk_bf16_f32 v185, v38, v54
	v_fma_f32 v37, -v153, v54, v37
	v_fmac_f32_e32 v53, v153, v38
	ds_write_b32 v174, v185 offset:1088
	v_fmac_f32_e32 v36, v152, v37
	v_fmac_f32_e32 v52, v152, v53
	v_cvt_pk_bf16_f32 v184, v37, v53
	v_fma_f32 v36, -v153, v53, v36
	v_fmac_f32_e32 v52, v153, v37
	ds_write_b32 v174, v184 offset:816
	v_fmac_f32_e32 v35, v152, v36
	v_fmac_f32_e32 v51, v152, v52
	v_cvt_pk_bf16_f32 v185, v36, v52
	v_fma_f32 v35, -v153, v52, v35
	v_fmac_f32_e32 v51, v153, v36
	ds_write_b32 v174, v185 offset:544
	v_fma_f32 v182, v152, v35, v34
	v_fma_f32 v178, v152, v51, v50
	v_cvt_pk_bf16_f32 v184, v35, v51
	v_fma_f32 v182, -v153, v51, v182
	v_fmac_f32_e32 v178, v153, v35
	ds_write_b32 v174, v184 offset:272
	v_cvt_pk_bf16_f32 v185, v182, v178
	ds_write_b32 v174, v185 offset:0
	s_add_u32 s28, s28, 1
	s_cmp_lt_u32 s28, 4
	s_cbranch_scc0 .LS5Q_wr0d1j3
	s_waitcnt vmcnt(2)
.LS5Q_wr0d1j3:
	s_waitcnt vmcnt(4)
	v_cvt_pk_bf16_f32 v212, v106, v107
	v_cvt_pk_bf16_f32 v213, v108, v109
	v_cvt_pk_bf16_f32 v214, v110, v111
	v_cvt_pk_bf16_f32 v215, v112, v113
	s_add_u32 s20, s28, 3
	s_cmp_lt_u32 s20, s52
	s_cselect_b64 s[58:59], s[50:51], 0
	v_lshl_add_u64 v[248:249], v[248:249], 0, s[58:59]
	global_load_dwordx4 v[110:113], v[248:249], off offset:16
	global_load_dwordx4 v[106:109], v[248:249], off
	ds_read_b128 v[216:219], v173 offset:60416
	ds_read_b128 v[220:223], v173 offset:60480
	ds_read_b128 v[224:227], v173 offset:60544
	ds_read_b128 v[228:231], v173 offset:60608
	v_fmac_f32_e32 v17, v152, v182
	v_fmac_f32_e32 v33, v152, v178
	v_fma_f32 v17, -v153, v178, v17
	v_fmac_f32_e32 v33, v153, v182
	v_mfma_f32_32x32x16_bf16 v[34:49], v[212:215], v[66:69], 0
	v_fmac_f32_e32 v16, v152, v17
	v_fmac_f32_e32 v32, v152, v33
	v_cvt_pk_bf16_f32 v184, v17, v33
	v_fma_f32 v16, -v153, v33, v16
	v_fmac_f32_e32 v32, v153, v17
	ds_write_b32 v174, v184 offset:64496
	v_fmac_f32_e32 v15, v152, v16
	v_fmac_f32_e32 v31, v152, v32
	v_cvt_pk_bf16_f32 v185, v16, v32
	v_fma_f32 v15, -v153, v32, v15
	v_fmac_f32_e32 v31, v153, v16
	ds_write_b32 v174, v185 offset:64224
	v_mfma_f32_32x32x16_bf16 v[50:65], v[212:215], v[74:77], 0
	v_fmac_f32_e32 v14, v152, v15
	v_fmac_f32_e32 v30, v152, v31
	v_cvt_pk_bf16_f32 v184, v15, v31
	v_fma_f32 v14, -v153, v31, v14
	v_fmac_f32_e32 v30, v153, v15
	ds_write_b32 v174, v184 offset:63952
	v_fmac_f32_e32 v13, v152, v14
	v_fmac_f32_e32 v29, v152, v30
	v_cvt_pk_bf16_f32 v185, v14, v30
	v_fma_f32 v13, -v153, v30, v13
	v_fmac_f32_e32 v29, v153, v14
	ds_write_b32 v174, v185 offset:63680
	s_waitcnt lgkmcnt(4)
	v_mfma_f32_16x16x32_bf16 v[232:235], v[82:85], v[216:219], 0
	v_fmac_f32_e32 v12, v152, v13
	v_fmac_f32_e32 v28, v152, v29
	v_cvt_pk_bf16_f32 v184, v13, v29
	v_fma_f32 v12, -v153, v29, v12
	v_fmac_f32_e32 v28, v153, v13
	ds_write_b32 v174, v184 offset:63408
	v_mfma_f32_16x16x32_bf16 v[232:235], v[86:89], v[220:223], v[232:235]
	v_fmac_f32_e32 v11, v152, v12
	v_fmac_f32_e32 v27, v152, v28
	v_cvt_pk_bf16_f32 v185, v12, v28
	v_fma_f32 v11, -v153, v28, v11
	v_fmac_f32_e32 v27, v153, v12
	ds_write_b32 v174, v185 offset:63136
	v_mfma_f32_16x16x32_bf16 v[232:235], v[90:93], v[224:227], v[232:235]
	v_fmac_f32_e32 v10, v152, v11
	v_fmac_f32_e32 v26, v152, v27
	v_cvt_pk_bf16_f32 v184, v11, v27
	v_fma_f32 v10, -v153, v27, v10
	v_fmac_f32_e32 v26, v153, v11
	ds_write_b32 v174, v184 offset:62864
	v_mfma_f32_16x16x32_bf16 v[232:235], v[94:97], v[228:231], v[232:235]
	v_fmac_f32_e32 v9, v152, v10
	v_fmac_f32_e32 v25, v152, v26
	v_cvt_pk_bf16_f32 v185, v10, v26
	v_fma_f32 v9, -v153, v26, v9
	v_fmac_f32_e32 v25, v153, v10
	ds_write_b32 v174, v185 offset:62592
	v_fmac_f32_e32 v8, v152, v9
	v_fmac_f32_e32 v24, v152, v25
	v_cvt_pk_bf16_f32 v184, v9, v25
	v_fma_f32 v8, -v153, v25, v8
	v_fmac_f32_e32 v24, v153, v9
	ds_write_b32 v174, v184 offset:62320
	v_fmac_f32_e32 v7, v152, v8
	v_fmac_f32_e32 v23, v152, v24
	v_cvt_pk_bf16_f32 v185, v8, v24
	v_fma_f32 v7, -v153, v24, v7
	v_fmac_f32_e32 v23, v153, v8
	ds_write_b32 v174, v185 offset:62048
	global_store_dwordx4 v[240:241], v[232:235], off
	v_lshl_add_u64 v[240:241], v[240:241], 0, s[50:51]
	v_fmac_f32_e32 v6, v152, v7
	v_fmac_f32_e32 v22, v152, v23
	v_cvt_pk_bf16_f32 v184, v7, v23
	v_fma_f32 v6, -v153, v23, v6
	v_fmac_f32_e32 v22, v153, v7
	ds_write_b32 v174, v184 offset:61776
	v_fmac_f32_e32 v5, v152, v6
	v_fmac_f32_e32 v21, v152, v22
	v_cvt_pk_bf16_f32 v185, v6, v22
	v_fma_f32 v5, -v153, v22, v5
	v_fmac_f32_e32 v21, v153, v6
	ds_write_b32 v174, v185 offset:61504
	v_fmac_f32_e32 v4, v152, v5
	v_fmac_f32_e32 v20, v152, v21
	v_cvt_pk_bf16_f32 v184, v5, v21
	v_fma_f32 v4, -v153, v21, v4
	v_fmac_f32_e32 v20, v153, v5
	ds_write_b32 v174, v184 offset:61232
	v_fmac_f32_e32 v3, v152, v4
	v_fmac_f32_e32 v19, v152, v20
	v_cvt_pk_bf16_f32 v185, v4, v20
	v_fma_f32 v3, -v153, v20, v3
	v_fmac_f32_e32 v19, v153, v4
	ds_write_b32 v174, v185 offset:60960
	v_fma_f32 v182, v152, v3, v2
	v_fma_f32 v178, v152, v19, v18
	v_cvt_pk_bf16_f32 v184, v3, v19
	v_fma_f32 v182, -v153, v19, v182
	v_fmac_f32_e32 v178, v153, v3
	ds_write_b32 v174, v184 offset:60688
	v_cvt_pk_bf16_f32 v185, v182, v178
	ds_write_b32 v174, v185 offset:60416
	s_waitcnt lgkmcnt(0)
	s_barrier
	s_add_u32 s28, s28, 1
	s_cmp_lt_u32 s28, s52
	s_cbranch_scc1 .LS5Q_loopr0d1
	s_branch .LS5Q_epi

.LS5Q_wr0d0j0:
	s_waitcnt vmcnt(4)
	v_cvt_pk_bf16_f32 v212, v102, v103
	v_cvt_pk_bf16_f32 v213, v104, v105
	v_cvt_pk_bf16_f32 v214, v98, v99
	v_cvt_pk_bf16_f32 v215, v100, v101
	s_add_u32 s20, s28, 3
	s_cmp_lt_u32 s20, s52
	s_cselect_b64 s[58:59], s[50:51], 0
	v_lshl_add_u64 v[248:249], v[248:249], 0, s[58:59]
	global_load_dwordx4 v[98:101], v[248:249], off offset:16
	global_load_dwordx4 v[102:105], v[248:249], off
	ds_read_b128 v[216:219], v175 offset:0
	ds_read_b128 v[220:223], v175 offset:64
	ds_read_b128 v[224:227], v175 offset:128
	ds_read_b128 v[228:231], v175 offset:192
	v_fmac_f32_e32 v34, v152, v182
	v_fmac_f32_e32 v50, v152, v178
	v_fma_f32 v34, -v153, v178, v34
	v_fmac_f32_e32 v50, v153, v182
	v_mfma_f32_32x32x16_bf16 v[2:17], v[212:215], v[66:69], 0
	v_fmac_f32_e32 v35, v152, v34
	v_fmac_f32_e32 v51, v152, v50
	v_cvt_pk_bf16_f32 v184, v34, v50
	v_fma_f32 v35, -v153, v50, v35
	v_fmac_f32_e32 v51, v153, v34
	ds_write_b32 v172, v184 offset:0
	v_fmac_f32_e32 v36, v152, v35
	v_fmac_f32_e32 v52, v152, v51
	v_cvt_pk_bf16_f32 v185, v35, v51
	v_fma_f32 v36, -v153, v51, v36
	v_fmac_f32_e32 v52, v153, v35
	ds_write_b32 v172, v185 offset:272
	v_mfma_f32_32x32x16_bf16 v[18:33], v[212:215], v[74:77], 0
	v_fmac_f32_e32 v37, v152, v36
	v_fmac_f32_e32 v53, v152, v52
	v_cvt_pk_bf16_f32 v184, v36, v52
	v_fma_f32 v37, -v153, v52, v37
	v_fmac_f32_e32 v53, v153, v36
	ds_write_b32 v172, v184 offset:544
	v_fmac_f32_e32 v38, v152, v37
	v_fmac_f32_e32 v54, v152, v53
	v_cvt_pk_bf16_f32 v185, v37, v53
	v_fma_f32 v38, -v153, v53, v38
	v_fmac_f32_e32 v54, v153, v37
	ds_write_b32 v172, v185 offset:816
	s_waitcnt lgkmcnt(4)
	v_mfma_f32_16x16x32_bf16 v[232:235], v[82:85], v[216:219], 0
	v_fmac_f32_e32 v39, v152, v38
	v_fmac_f32_e32 v55, v152, v54
	v_cvt_pk_bf16_f32 v184, v38, v54
	v_fma_f32 v39, -v153, v54, v39
	v_fmac_f32_e32 v55, v153, v38
	ds_write_b32 v172, v184 offset:1088
	v_mfma_f32_16x16x32_bf16 v[232:235], v[86:89], v[220:223], v[232:235]
	v_fmac_f32_e32 v40, v152, v39
	v_fmac_f32_e32 v56, v152, v55
	v_cvt_pk_bf16_f32 v185, v39, v55
	v_fma_f32 v40, -v153, v55, v40
	v_fmac_f32_e32 v56, v153, v39
	ds_write_b32 v172, v185 offset:1360
	v_mfma_f32_16x16x32_bf16 v[232:235], v[90:93], v[224:227], v[232:235]
	v_fmac_f32_e32 v41, v152, v40
	v_fmac_f32_e32 v57, v152, v56
	v_cvt_pk_bf16_f32 v184, v40, v56
	v_fma_f32 v41, -v153, v56, v41
	v_fmac_f32_e32 v57, v153, v40
	ds_write_b32 v172, v184 offset:1632
	v_mfma_f32_16x16x32_bf16 v[232:235], v[94:97], v[228:231], v[232:235]
	v_fmac_f32_e32 v42, v152, v41
	v_fmac_f32_e32 v58, v152, v57
	v_cvt_pk_bf16_f32 v185, v41, v57
	v_fma_f32 v42, -v153, v57, v42
	v_fmac_f32_e32 v58, v153, v41
	ds_write_b32 v172, v185 offset:1904
	v_fmac_f32_e32 v43, v152, v42
	v_fmac_f32_e32 v59, v152, v58
	v_cvt_pk_bf16_f32 v184, v42, v58
	v_fma_f32 v43, -v153, v58, v43
	v_fmac_f32_e32 v59, v153, v42
	ds_write_b32 v172, v184 offset:2176
	v_fmac_f32_e32 v44, v152, v43
	v_fmac_f32_e32 v60, v152, v59
	v_cvt_pk_bf16_f32 v185, v43, v59
	v_fma_f32 v44, -v153, v59, v44
	v_fmac_f32_e32 v60, v153, v43
	ds_write_b32 v172, v185 offset:2448
	s_cmp_lt_u32 s28, 2
	s_cbranch_scc1 .LS5Q_nstr0d0j0
	global_store_dwordx4 v[240:241], v[232:235], off
	v_lshl_add_u64 v[240:241], v[240:241], 0, s[50:51]
.LS5Q_nstr0d0j0:
	v_fmac_f32_e32 v45, v152, v44
	v_fmac_f32_e32 v61, v152, v60
	v_cvt_pk_bf16_f32 v184, v44, v60
	v_fma_f32 v45, -v153, v60, v45
	v_fmac_f32_e32 v61, v153, v44
	ds_write_b32 v172, v184 offset:2720
	v_fmac_f32_e32 v46, v152, v45
	v_fmac_f32_e32 v62, v152, v61
	v_cvt_pk_bf16_f32 v185, v45, v61
	v_fma_f32 v46, -v153, v61, v46
	v_fmac_f32_e32 v62, v153, v45
	ds_write_b32 v172, v185 offset:2992
	v_fmac_f32_e32 v47, v152, v46
	v_fmac_f32_e32 v63, v152, v62
	v_cvt_pk_bf16_f32 v184, v46, v62
	v_fma_f32 v47, -v153, v62, v47
	v_fmac_f32_e32 v63, v153, v46
	ds_write_b32 v172, v184 offset:3264
	v_fmac_f32_e32 v48, v152, v47
	v_fmac_f32_e32 v64, v152, v63
	v_cvt_pk_bf16_f32 v185, v47, v63
	v_fma_f32 v48, -v153, v63, v48
	v_fmac_f32_e32 v64, v153, v47
	ds_write_b32 v172, v185 offset:3536
	v_fma_f32 v182, v152, v48, v49
	v_fma_f32 v178, v152, v64, v65
	v_cvt_pk_bf16_f32 v184, v48, v64
	v_fma_f32 v182, -v153, v64, v182
	v_fmac_f32_e32 v178, v153, v48
	ds_write_b32 v172, v184 offset:3808
	v_cvt_pk_bf16_f32 v185, v182, v178
	ds_write_b32 v172, v185 offset:4080
	s_add_u32 s28, s28, 1
	s_cmp_lt_u32 s28, 4
	s_cbranch_scc0 .LS5Q_wr0d0j1
	s_waitcnt vmcnt(2)
.LS5Q_wr0d0j1:
	s_waitcnt vmcnt(4)
	v_cvt_pk_bf16_f32 v212, v106, v107
	v_cvt_pk_bf16_f32 v213, v108, v109
	v_cvt_pk_bf16_f32 v214, v110, v111
	v_cvt_pk_bf16_f32 v215, v112, v113
	s_add_u32 s20, s28, 3
	s_cmp_lt_u32 s20, s52
	s_cselect_b64 s[58:59], s[50:51], 0
	v_lshl_add_u64 v[248:249], v[248:249], 0, s[58:59]
	global_load_dwordx4 v[110:113], v[248:249], off offset:16
	global_load_dwordx4 v[106:109], v[248:249], off
	ds_read_b128 v[216:219], v175 offset:60416
	ds_read_b128 v[220:223], v175 offset:60480
	ds_read_b128 v[224:227], v175 offset:60544
	ds_read_b128 v[228:231], v175 offset:60608
	v_fmac_f32_e32 v2, v152, v182
	v_fmac_f32_e32 v18, v152, v178
	v_fma_f32 v2, -v153, v178, v2
	v_fmac_f32_e32 v18, v153, v182
	v_mfma_f32_32x32x16_bf16 v[34:49], v[212:215], v[66:69], 0
	v_fmac_f32_e32 v3, v152, v2
	v_fmac_f32_e32 v19, v152, v18
	v_cvt_pk_bf16_f32 v184, v2, v18
	v_fma_f32 v3, -v153, v18, v3
	v_fmac_f32_e32 v19, v153, v2
	ds_write_b32 v172, v184 offset:60416
	v_fmac_f32_e32 v4, v152, v3
	v_fmac_f32_e32 v20, v152, v19
	v_cvt_pk_bf16_f32 v185, v3, v19
	v_fma_f32 v4, -v153, v19, v4
	v_fmac_f32_e32 v20, v153, v3
	ds_write_b32 v172, v185 offset:60688
	v_mfma_f32_32x32x16_bf16 v[50:65], v[212:215], v[74:77], 0
	v_fmac_f32_e32 v5, v152, v4
	v_fmac_f32_e32 v21, v152, v20
	v_cvt_pk_bf16_f32 v184, v4, v20
	v_fma_f32 v5, -v153, v20, v5
	v_fmac_f32_e32 v21, v153, v4
	ds_write_b32 v172, v184 offset:60960
	v_fmac_f32_e32 v6, v152, v5
	v_fmac_f32_e32 v22, v152, v21
	v_cvt_pk_bf16_f32 v185, v5, v21
	v_fma_f32 v6, -v153, v21, v6
	v_fmac_f32_e32 v22, v153, v5
	ds_write_b32 v172, v185 offset:61232
	s_waitcnt lgkmcnt(4)
	v_mfma_f32_16x16x32_bf16 v[232:235], v[82:85], v[216:219], 0
	v_fmac_f32_e32 v7, v152, v6
	v_fmac_f32_e32 v23, v152, v22
	v_cvt_pk_bf16_f32 v184, v6, v22
	v_fma_f32 v7, -v153, v22, v7
	v_fmac_f32_e32 v23, v153, v6
	ds_write_b32 v172, v184 offset:61504
	v_mfma_f32_16x16x32_bf16 v[232:235], v[86:89], v[220:223], v[232:235]
	v_fmac_f32_e32 v8, v152, v7
	v_fmac_f32_e32 v24, v152, v23
	v_cvt_pk_bf16_f32 v185, v7, v23
	v_fma_f32 v8, -v153, v23, v8
	v_fmac_f32_e32 v24, v153, v7
	ds_write_b32 v172, v185 offset:61776
	v_mfma_f32_16x16x32_bf16 v[232:235], v[90:93], v[224:227], v[232:235]
	v_fmac_f32_e32 v9, v152, v8
	v_fmac_f32_e32 v25, v152, v24
	v_cvt_pk_bf16_f32 v184, v8, v24
	v_fma_f32 v9, -v153, v24, v9
	v_fmac_f32_e32 v25, v153, v8
	ds_write_b32 v172, v184 offset:62048
	v_mfma_f32_16x16x32_bf16 v[232:235], v[94:97], v[228:231], v[232:235]
	v_fmac_f32_e32 v10, v152, v9
	v_fmac_f32_e32 v26, v152, v25
	v_cvt_pk_bf16_f32 v185, v9, v25
	v_fma_f32 v10, -v153, v25, v10
	v_fmac_f32_e32 v26, v153, v9
	ds_write_b32 v172, v185 offset:62320
	v_fmac_f32_e32 v11, v152, v10
	v_fmac_f32_e32 v27, v152, v26
	v_cvt_pk_bf16_f32 v184, v10, v26
	v_fma_f32 v11, -v153, v26, v11
	v_fmac_f32_e32 v27, v153, v10
	ds_write_b32 v172, v184 offset:62592
	v_fmac_f32_e32 v12, v152, v11
	v_fmac_f32_e32 v28, v152, v27
	v_cvt_pk_bf16_f32 v185, v11, v27
	v_fma_f32 v12, -v153, v27, v12
	v_fmac_f32_e32 v28, v153, v11
	ds_write_b32 v172, v185 offset:62864
	s_cmp_lt_u32 s28, 2
	s_cbranch_scc1 .LS5Q_nstr0d0j1
	global_store_dwordx4 v[240:241], v[232:235], off
	v_lshl_add_u64 v[240:241], v[240:241], 0, s[50:51]
.LS5Q_nstr0d0j1:
	v_fmac_f32_e32 v13, v152, v12
	v_fmac_f32_e32 v29, v152, v28
	v_cvt_pk_bf16_f32 v184, v12, v28
	v_fma_f32 v13, -v153, v28, v13
	v_fmac_f32_e32 v29, v153, v12
	ds_write_b32 v172, v184 offset:63136
	v_fmac_f32_e32 v14, v152, v13
	v_fmac_f32_e32 v30, v152, v29
	v_cvt_pk_bf16_f32 v185, v13, v29
	v_fma_f32 v14, -v153, v29, v14
	v_fmac_f32_e32 v30, v153, v13
	ds_write_b32 v172, v185 offset:63408
	v_fmac_f32_e32 v15, v152, v14
	v_fmac_f32_e32 v31, v152, v30
	v_cvt_pk_bf16_f32 v184, v14, v30
	v_fma_f32 v15, -v153, v30, v15
	v_fmac_f32_e32 v31, v153, v14
	ds_write_b32 v172, v184 offset:63680
	v_fmac_f32_e32 v16, v152, v15
	v_fmac_f32_e32 v32, v152, v31
	v_cvt_pk_bf16_f32 v185, v15, v31
	v_fma_f32 v16, -v153, v31, v16
	v_fmac_f32_e32 v32, v153, v15
	ds_write_b32 v172, v185 offset:63952
	v_fma_f32 v182, v152, v16, v17
	v_fma_f32 v178, v152, v32, v33
	v_cvt_pk_bf16_f32 v184, v16, v32
	v_fma_f32 v182, -v153, v32, v182
	v_fmac_f32_e32 v178, v153, v16
	ds_write_b32 v172, v184 offset:64224
	v_cvt_pk_bf16_f32 v185, v182, v178
	ds_write_b32 v172, v185 offset:64496
	s_waitcnt lgkmcnt(0)
	s_barrier
	s_add_u32 s28, s28, 1
	s_cmp_lt_u32 s28, 4
	s_cbranch_scc0 .LS5Q_wr0d0j2
	s_waitcnt vmcnt(2)
.LS5Q_wr0d0j2:
	s_waitcnt vmcnt(4)
	v_cvt_pk_bf16_f32 v212, v102, v103
	v_cvt_pk_bf16_f32 v213, v104, v105
	v_cvt_pk_bf16_f32 v214, v98, v99
	v_cvt_pk_bf16_f32 v215, v100, v101
	s_add_u32 s20, s28, 3
	s_cmp_lt_u32 s20, s52
	s_cselect_b64 s[58:59], s[50:51], 0
	v_lshl_add_u64 v[248:249], v[248:249], 0, s[58:59]
	global_load_dwordx4 v[98:101], v[248:249], off offset:16
	global_load_dwordx4 v[102:105], v[248:249], off
	ds_read_b128 v[216:219], v173 offset:0
	ds_read_b128 v[220:223], v173 offset:64
	ds_read_b128 v[224:227], v173 offset:128
	ds_read_b128 v[228:231], v173 offset:192
	v_fmac_f32_e32 v34, v152, v182
	v_fmac_f32_e32 v50, v152, v178
	v_fma_f32 v34, -v153, v178, v34
	v_fmac_f32_e32 v50, v153, v182
	v_mfma_f32_32x32x16_bf16 v[2:17], v[212:215], v[66:69], 0
	v_fmac_f32_e32 v35, v152, v34
	v_fmac_f32_e32 v51, v152, v50
	v_cvt_pk_bf16_f32 v184, v34, v50
	v_fma_f32 v35, -v153, v50, v35
	v_fmac_f32_e32 v51, v153, v34
	ds_write_b32 v174, v184 offset:0
	v_fmac_f32_e32 v36, v152, v35
	v_fmac_f32_e32 v52, v152, v51
	v_cvt_pk_bf16_f32 v185, v35, v51
	v_fma_f32 v36, -v153, v51, v36
	v_fmac_f32_e32 v52, v153, v35
	ds_write_b32 v174, v185 offset:272
	v_mfma_f32_32x32x16_bf16 v[18:33], v[212:215], v[74:77], 0
	v_fmac_f32_e32 v37, v152, v36
	v_fmac_f32_e32 v53, v152, v52
	v_cvt_pk_bf16_f32 v184, v36, v52
	v_fma_f32 v37, -v153, v52, v37
	v_fmac_f32_e32 v53, v153, v36
	ds_write_b32 v174, v184 offset:544
	v_fmac_f32_e32 v38, v152, v37
	v_fmac_f32_e32 v54, v152, v53
	v_cvt_pk_bf16_f32 v185, v37, v53
	v_fma_f32 v38, -v153, v53, v38
	v_fmac_f32_e32 v54, v153, v37
	ds_write_b32 v174, v185 offset:816
	s_waitcnt lgkmcnt(4)
	v_mfma_f32_16x16x32_bf16 v[232:235], v[82:85], v[216:219], 0
	v_fmac_f32_e32 v39, v152, v38
	v_fmac_f32_e32 v55, v152, v54
	v_cvt_pk_bf16_f32 v184, v38, v54
	v_fma_f32 v39, -v153, v54, v39
	v_fmac_f32_e32 v55, v153, v38
	ds_write_b32 v174, v184 offset:1088
	v_mfma_f32_16x16x32_bf16 v[232:235], v[86:89], v[220:223], v[232:235]
	v_fmac_f32_e32 v40, v152, v39
	v_fmac_f32_e32 v56, v152, v55
	v_cvt_pk_bf16_f32 v185, v39, v55
	v_fma_f32 v40, -v153, v55, v40
	v_fmac_f32_e32 v56, v153, v39
	ds_write_b32 v174, v185 offset:1360
	v_mfma_f32_16x16x32_bf16 v[232:235], v[90:93], v[224:227], v[232:235]
	v_fmac_f32_e32 v41, v152, v40
	v_fmac_f32_e32 v57, v152, v56
	v_cvt_pk_bf16_f32 v184, v40, v56
	v_fma_f32 v41, -v153, v56, v41
	v_fmac_f32_e32 v57, v153, v40
	ds_write_b32 v174, v184 offset:1632
	v_mfma_f32_16x16x32_bf16 v[232:235], v[94:97], v[228:231], v[232:235]
	v_fmac_f32_e32 v42, v152, v41
	v_fmac_f32_e32 v58, v152, v57
	v_cvt_pk_bf16_f32 v185, v41, v57
	v_fma_f32 v42, -v153, v57, v42
	v_fmac_f32_e32 v58, v153, v41
	ds_write_b32 v174, v185 offset:1904
	v_fmac_f32_e32 v43, v152, v42
	v_fmac_f32_e32 v59, v152, v58
	v_cvt_pk_bf16_f32 v184, v42, v58
	v_fma_f32 v43, -v153, v58, v43
	v_fmac_f32_e32 v59, v153, v42
	ds_write_b32 v174, v184 offset:2176
	v_fmac_f32_e32 v44, v152, v43
	v_fmac_f32_e32 v60, v152, v59
	v_cvt_pk_bf16_f32 v185, v43, v59
	v_fma_f32 v44, -v153, v59, v44
	v_fmac_f32_e32 v60, v153, v43
	ds_write_b32 v174, v185 offset:2448
	global_store_dwordx4 v[240:241], v[232:235], off
	v_lshl_add_u64 v[240:241], v[240:241], 0, s[50:51]
	v_fmac_f32_e32 v45, v152, v44
	v_fmac_f32_e32 v61, v152, v60
	v_cvt_pk_bf16_f32 v184, v44, v60
	v_fma_f32 v45, -v153, v60, v45
	v_fmac_f32_e32 v61, v153, v44
	ds_write_b32 v174, v184 offset:2720
	v_fmac_f32_e32 v46, v152, v45
	v_fmac_f32_e32 v62, v152, v61
	v_cvt_pk_bf16_f32 v185, v45, v61
	v_fma_f32 v46, -v153, v61, v46
	v_fmac_f32_e32 v62, v153, v45
	ds_write_b32 v174, v185 offset:2992
	v_fmac_f32_e32 v47, v152, v46
	v_fmac_f32_e32 v63, v152, v62
	v_cvt_pk_bf16_f32 v184, v46, v62
	v_fma_f32 v47, -v153, v62, v47
	v_fmac_f32_e32 v63, v153, v46
	ds_write_b32 v174, v184 offset:3264
	v_fmac_f32_e32 v48, v152, v47
	v_fmac_f32_e32 v64, v152, v63
	v_cvt_pk_bf16_f32 v185, v47, v63
	v_fma_f32 v48, -v153, v63, v48
	v_fmac_f32_e32 v64, v153, v47
	ds_write_b32 v174, v185 offset:3536
	v_fma_f32 v182, v152, v48, v49
	v_fma_f32 v178, v152, v64, v65
	v_cvt_pk_bf16_f32 v184, v48, v64
	v_fma_f32 v182, -v153, v64, v182
	v_fmac_f32_e32 v178, v153, v48
	ds_write_b32 v174, v184 offset:3808
	v_cvt_pk_bf16_f32 v185, v182, v178
	ds_write_b32 v174, v185 offset:4080
	s_add_u32 s28, s28, 1
	s_cmp_lt_u32 s28, 4
	s_cbranch_scc0 .LS5Q_wr0d0j3
	s_waitcnt vmcnt(2)
.LS5Q_wr0d0j3:
	s_waitcnt vmcnt(4)
	v_cvt_pk_bf16_f32 v212, v106, v107
	v_cvt_pk_bf16_f32 v213, v108, v109
	v_cvt_pk_bf16_f32 v214, v110, v111
	v_cvt_pk_bf16_f32 v215, v112, v113
	s_add_u32 s20, s28, 3
	s_cmp_lt_u32 s20, s52
	s_cselect_b64 s[58:59], s[50:51], 0
	v_lshl_add_u64 v[248:249], v[248:249], 0, s[58:59]
	global_load_dwordx4 v[110:113], v[248:249], off offset:16
	global_load_dwordx4 v[106:109], v[248:249], off
	ds_read_b128 v[216:219], v173 offset:60416
	ds_read_b128 v[220:223], v173 offset:60480
	ds_read_b128 v[224:227], v173 offset:60544
	ds_read_b128 v[228:231], v173 offset:60608
	v_fmac_f32_e32 v2, v152, v182
	v_fmac_f32_e32 v18, v152, v178
	v_fma_f32 v2, -v153, v178, v2
	v_fmac_f32_e32 v18, v153, v182
	v_mfma_f32_32x32x16_bf16 v[34:49], v[212:215], v[66:69], 0
	v_fmac_f32_e32 v3, v152, v2
	v_fmac_f32_e32 v19, v152, v18
	v_cvt_pk_bf16_f32 v184, v2, v18
	v_fma_f32 v3, -v153, v18, v3
	v_fmac_f32_e32 v19, v153, v2
	ds_write_b32 v174, v184 offset:60416
	v_fmac_f32_e32 v4, v152, v3
	v_fmac_f32_e32 v20, v152, v19
	v_cvt_pk_bf16_f32 v185, v3, v19
	v_fma_f32 v4, -v153, v19, v4
	v_fmac_f32_e32 v20, v153, v3
	ds_write_b32 v174, v185 offset:60688
	v_mfma_f32_32x32x16_bf16 v[50:65], v[212:215], v[74:77], 0
	v_fmac_f32_e32 v5, v152, v4
	v_fmac_f32_e32 v21, v152, v20
	v_cvt_pk_bf16_f32 v184, v4, v20
	v_fma_f32 v5, -v153, v20, v5
	v_fmac_f32_e32 v21, v153, v4
	ds_write_b32 v174, v184 offset:60960
	v_fmac_f32_e32 v6, v152, v5
	v_fmac_f32_e32 v22, v152, v21
	v_cvt_pk_bf16_f32 v185, v5, v21
	v_fma_f32 v6, -v153, v21, v6
	v_fmac_f32_e32 v22, v153, v5
	ds_write_b32 v174, v185 offset:61232
	s_waitcnt lgkmcnt(4)
	v_mfma_f32_16x16x32_bf16 v[232:235], v[82:85], v[216:219], 0
	v_fmac_f32_e32 v7, v152, v6
	v_fmac_f32_e32 v23, v152, v22
	v_cvt_pk_bf16_f32 v184, v6, v22
	v_fma_f32 v7, -v153, v22, v7
	v_fmac_f32_e32 v23, v153, v6
	ds_write_b32 v174, v184 offset:61504
	v_mfma_f32_16x16x32_bf16 v[232:235], v[86:89], v[220:223], v[232:235]
	v_fmac_f32_e32 v8, v152, v7
	v_fmac_f32_e32 v24, v152, v23
	v_cvt_pk_bf16_f32 v185, v7, v23
	v_fma_f32 v8, -v153, v23, v8
	v_fmac_f32_e32 v24, v153, v7
	ds_write_b32 v174, v185 offset:61776
	v_mfma_f32_16x16x32_bf16 v[232:235], v[90:93], v[224:227], v[232:235]
	v_fmac_f32_e32 v9, v152, v8
	v_fmac_f32_e32 v25, v152, v24
	v_cvt_pk_bf16_f32 v184, v8, v24
	v_fma_f32 v9, -v153, v24, v9
	v_fmac_f32_e32 v25, v153, v8
	ds_write_b32 v174, v184 offset:62048
	v_mfma_f32_16x16x32_bf16 v[232:235], v[94:97], v[228:231], v[232:235]
	v_fmac_f32_e32 v10, v152, v9
	v_fmac_f32_e32 v26, v152, v25
	v_cvt_pk_bf16_f32 v185, v9, v25
	v_fma_f32 v10, -v153, v25, v10
	v_fmac_f32_e32 v26, v153, v9
	ds_write_b32 v174, v185 offset:62320
	v_fmac_f32_e32 v11, v152, v10
	v_fmac_f32_e32 v27, v152, v26
	v_cvt_pk_bf16_f32 v184, v10, v26
	v_fma_f32 v11, -v153, v26, v11
	v_fmac_f32_e32 v27, v153, v10
	ds_write_b32 v174, v184 offset:62592
	v_fmac_f32_e32 v12, v152, v11
	v_fmac_f32_e32 v28, v152, v27
	v_cvt_pk_bf16_f32 v185, v11, v27
	v_fma_f32 v12, -v153, v27, v12
	v_fmac_f32_e32 v28, v153, v11
	ds_write_b32 v174, v185 offset:62864
	global_store_dwordx4 v[240:241], v[232:235], off
	v_lshl_add_u64 v[240:241], v[240:241], 0, s[50:51]
	v_fmac_f32_e32 v13, v152, v12
	v_fmac_f32_e32 v29, v152, v28
	v_cvt_pk_bf16_f32 v184, v12, v28
	v_fma_f32 v13, -v153, v28, v13
	v_fmac_f32_e32 v29, v153, v12
	ds_write_b32 v174, v184 offset:63136
	v_fmac_f32_e32 v14, v152, v13
	v_fmac_f32_e32 v30, v152, v29
	v_cvt_pk_bf16_f32 v185, v13, v29
	v_fma_f32 v14, -v153, v29, v14
	v_fmac_f32_e32 v30, v153, v13
	ds_write_b32 v174, v185 offset:63408
	v_fmac_f32_e32 v15, v152, v14
	v_fmac_f32_e32 v31, v152, v30
	v_cvt_pk_bf16_f32 v184, v14, v30
	v_fma_f32 v15, -v153, v30, v15
	v_fmac_f32_e32 v31, v153, v14
	ds_write_b32 v174, v184 offset:63680
	v_fmac_f32_e32 v16, v152, v15
	v_fmac_f32_e32 v32, v152, v31
	v_cvt_pk_bf16_f32 v185, v15, v31
	v_fma_f32 v16, -v153, v31, v16
	v_fmac_f32_e32 v32, v153, v15
	ds_write_b32 v174, v185 offset:63952
	v_fma_f32 v182, v152, v16, v17
	v_fma_f32 v178, v152, v32, v33
	v_cvt_pk_bf16_f32 v184, v16, v32
	v_fma_f32 v182, -v153, v32, v182
	v_fmac_f32_e32 v178, v153, v16
	ds_write_b32 v174, v184 offset:64224
	v_cvt_pk_bf16_f32 v185, v182, v178
	ds_write_b32 v174, v185 offset:64496
	s_waitcnt lgkmcnt(0)
	s_barrier
	s_add_u32 s28, s28, 1
	s_cmp_lt_u32 s28, s52
	s_cbranch_scc1 .LS5Q_loopr0d0
	s_branch .LS5Q_epi
.LS5Q_epi:
	ds_read_b128 v[216:219], v175 offset:0
	ds_read_b128 v[220:223], v175 offset:64
	ds_read_b128 v[224:227], v175 offset:128
	ds_read_b128 v[228:231], v175 offset:192
	s_waitcnt lgkmcnt(0)
	v_mfma_f32_16x16x32_bf16 v[232:235], v[82:85], v[216:219], 0
	v_mfma_f32_16x16x32_bf16 v[232:235], v[86:89], v[220:223], v[232:235]
	v_mfma_f32_16x16x32_bf16 v[232:235], v[90:93], v[224:227], v[232:235]
	v_mfma_f32_16x16x32_bf16 v[232:235], v[94:97], v[228:231], v[232:235]
	s_nop 7
	global_store_dwordx4 v[240:241], v[232:235], off
	v_lshl_add_u64 v[240:241], v[240:241], 0, s[50:51]
	ds_read_b128 v[216:219], v175 offset:60416
	ds_read_b128 v[220:223], v175 offset:60480
	ds_read_b128 v[224:227], v175 offset:60544
	ds_read_b128 v[228:231], v175 offset:60608
	s_waitcnt lgkmcnt(0)
	v_mfma_f32_16x16x32_bf16 v[232:235], v[82:85], v[216:219], 0
	v_mfma_f32_16x16x32_bf16 v[232:235], v[86:89], v[220:223], v[232:235]
	v_mfma_f32_16x16x32_bf16 v[232:235], v[90:93], v[224:227], v[232:235]
	v_mfma_f32_16x16x32_bf16 v[232:235], v[94:97], v[228:231], v[232:235]
	s_nop 7
	global_store_dwordx4 v[240:241], v[232:235], off

.LBB0_448:
	v_readlane_b32 s2, v251, 0
	s_cmp_ge_i32 s2, s78
	s_cbranch_scc1 .LBB0_511
	s_lshl_b64 s[2:3], s[0:1], 17
	s_lshl_b64 s[20:21], s[0:1], 21
	s_mul_hi_i32 s28, s0, 0x580000
	s_mul_i32 s34, s0, 0x580000
	s_lshl_b32 s0, s96, 1
	v_readlane_b32 s4, v253, 33
	s_or_b32 s0, s0, s92
	v_readlane_b32 s8, v253, 37
	s_mul_hi_i32 s40, s0, 0x580000
	s_mul_i32 s41, s0, 0x580000
	s_mul_hi_i32 s42, s0, 0xb00000
	s_mul_i32 s43, s0, 0xb00000
	v_readlane_b32 s5, v253, 34
	v_readlane_b32 s6, v253, 35
	v_readlane_b32 s7, v253, 36
	v_readlane_b32 s9, v253, 38
	v_readlane_b32 s10, v253, 39
	v_readlane_b32 s11, v253, 40
	s_mov_b64 s[0:1], s[36:37]
	s_add_u32 s36, s8, s2
	s_addc_u32 s37, s9, s3
	v_readlane_b32 s4, v254, 1
	s_lshl_b64 s[0:1], s[0:1], 2
	v_readlane_b32 s6, v254, 3
	v_readlane_b32 s7, v254, 4
	s_add_u32 s0, s6, s0
	s_addc_u32 s1, s7, s1
	v_readlane_b32 s44, v251, 38
	v_writelane_b32 v255, s0, 6
	v_readlane_b32 s58, v251, 52
	v_readlane_b32 s59, v251, 53
	v_writelane_b32 v255, s1, 7
	s_add_u32 s0, s58, s20
	v_readlane_b32 s56, v251, 50
	s_addc_u32 s1, s59, s21
	v_readlane_b32 s57, v251, 51
	s_add_u32 s60, s56, s20
	v_readlane_b32 s54, v251, 48
	s_addc_u32 s61, s57, s21
	v_readlane_b32 s55, v251, 49
	s_add_u32 s62, s54, s20
	v_and_b32_e32 v133, 31, v203
	s_waitcnt vmcnt(5)
	v_mul_i32_i24_e32 v5, 0x60, v201
	v_readlane_b32 s52, v251, 46
	s_addc_u32 s63, s55, s21
	s_waitcnt vmcnt(4)
	v_or_b32_e32 v6, v5, v133
	v_readlane_b32 s53, v251, 47
	s_add_u32 s64, s52, s20
	v_lshlrev_b32_e32 v4, 4, v203
	v_lshlrev_b32_e32 v138, 7, v6
	v_lshlrev_b32_e32 v6, 7, v203
	v_readlane_b32 s50, v251, 44
	s_addc_u32 s65, s53, s21
	v_lshrrev_b32_e32 v2, 5, v203
	v_and_b32_e32 v4, 0xfffffc00, v4
	v_and_b32_e32 v140, 0x6f80, v6
	v_bfe_u32 v6, v203, 1, 3
	v_readlane_b32 s51, v251, 45
	s_add_u32 s66, s50, s34
	v_add_u32_e32 v137, 32, v4
	v_bfe_u32 v4, v203, 5, 1
	v_bitop3_b32 v2, v2, v6, 1 bitop3:0x6c
	v_readlane_b32 s48, v251, 42
	s_addc_u32 s67, s51, s28
	v_lshrrev_b32_e32 v3, 4, v203
	v_lshlrev_b32_e32 v141, 4, v2
	v_bitop3_b32 v2, v4, v6, 2 bitop3:0x36
	v_readlane_b32 s49, v251, 43
	s_add_u32 s68, s48, s41
	v_xor_b32_e32 v0, v3, v203
	v_lshlrev_b32_e32 v142, 4, v2
	v_bitop3_b32 v2, v4, v6, 4 bitop3:0x36
	v_readlane_b32 s46, v251, 40
	s_addc_u32 s69, s49, s40
	v_lshlrev_b32_e32 v0, 3, v0
	v_lshlrev_b32_e32 v143, 4, v2
	v_bitop3_b32 v2, v4, v6, 6 bitop3:0x36
	v_readlane_b32 s47, v251, 41
	s_add_u32 s46, s46, s43
	v_and_b32_e32 v0, 56, v0
	v_lshlrev_b32_e32 v144, 4, v2
	v_and_b32_e32 v146, 1, v203
	v_bitop3_b32 v2, v3, 7, v203 bitop3:0x48
	v_readlane_b32 s92, v251, 0
	s_mov_b64 s[50:51], s[0:1]
	s_addc_u32 s47, s47, s42
	v_ashrrev_i32_e32 v136, 3, v203
	v_and_b32_e32 v139, 0xc0, v203
	v_lshl_or_b32 v145, v4, 2, v5
	v_cmp_eq_u32_e64 s[40:41], 0, v146
	v_and_b32_e32 v147, 30, v203
	v_lshlrev_b32_e32 v98, 4, v2
	v_mov_b32_e32 v99, v1
	v_lshlrev_b32_e32 v0, 1, v0
	s_mov_b32 s79, s92
	v_readlane_b32 s12, v253, 41
	v_readlane_b32 s13, v253, 42
	v_readlane_b32 s14, v253, 43
	v_readlane_b32 s15, v253, 44
	v_readlane_b32 s16, v253, 45
	v_readlane_b32 s17, v253, 46
	v_readlane_b32 s18, v253, 47
	v_readlane_b32 s19, v253, 48
	v_readlane_b32 s5, v254, 2
	v_readlane_b32 s8, v254, 5
	v_readlane_b32 s9, v254, 6
	v_readlane_b32 s10, v254, 7
	v_readlane_b32 s11, v254, 8
	v_readlane_b32 s45, v251, 39
	s_waitcnt vmcnt(0)
	s_branch .LBB0_451
.Ltr_7:
	s_branch .LBB0_7

.Ltr_9:
	s_branch .LBB0_9
.LBB0_450:
	v_readlane_b32 s0, v251, 5
	s_add_i32 s92, s92, s0
	s_add_i32 s79, s79, s0
	s_cmp_ge_i32 s92, s78
	v_readlane_b32 s1, v251, 6
	s_cbranch_scc1 .LBB0_511
